# remaining ds_bpermute butterflies -> DPP: C item LayerNorm stats (quad_perm) and the P0 row sum-of-squares / rsw reductions
# speedup vs baseline: 1.0048x; 1.0003x over previous
.LBB0_27:
	s_or_b64 exec, exec, s[16:17]
	s_nop 1
	v_add_f32_dpp v15, v15, v15 quad_perm:[1,0,3,2] row_mask:0xf bank_mask:0xf
	s_nop 1
	v_add_f32_dpp v15, v15, v15 quad_perm:[2,3,0,1] row_mask:0xf bank_mask:0xf
	s_nop 1
	v_add_f32_dpp v15, v15, v15 row_half_mirror row_mask:0xf bank_mask:0xf
	s_nop 1
	v_add_f32_dpp v15, v15, v15 row_mirror row_mask:0xf bank_mask:0xf
	s_nop 1
	v_add_f32_dpp v15, v15, v15 row_bcast:15 row_mask:0xa bank_mask:0xf
	s_nop 1
	v_add_f32_dpp v15, v15, v15 row_bcast:31 row_mask:0xc bank_mask:0xf
	s_nop 1
	v_readlane_b32 s16, v15, 63
	v_mov_b32_e32 v16, 0
	s_nop 0
	v_mov_b32_e32 v15, s16
	s_and_saveexec_b64 s[0:1], vcc
	s_cbranch_execz .LBB0_22
	s_waitcnt lgkmcnt(0)
	v_add_f32_e32 v15, v15, v16
	global_store_dword v[4:5], v15, off
	s_branch .LBB0_22

.LBB0_201:
	v_cmp_lt_i32_e64 s[0:1], s7, v2
	v_mov_b64_e32 v[20:21], v[2:3]
	v_mov_b64_e32 v[22:23], v[8:9]
	s_and_saveexec_b64 s[2:3], s[0:1]
	v_add_u32_e32 v4, 0xffffc000, v2
	v_lshlrev_b64 v[20:21], 12, v[4:5]
	v_mov_b32_e32 v4, v2
	v_lshl_add_u64 v[22:23], s[66:67], 0, v[20:21]
	v_mov_b64_e32 v[20:21], v[4:5]
	s_or_b64 exec, exec, s[2:3]
	v_lshl_add_u64 v[38:39], v[22:23], 0, s[20:21]
	s_waitcnt lgkmcnt(0)
	v_lshl_add_u64 v[24:25], v[22:23], 0, v[12:13]
	v_lshl_add_u64 v[58:59], v[38:39], 0, v[16:17]
	global_load_dwordx4 v[34:37], v[24:25], off nt
	global_load_dwordx4 v[42:45], v[24:25], off offset:1024 nt
	global_load_dwordx4 v[46:49], v[24:25], off offset:2048 nt
	v_lshl_add_u64 v[50:51], v[38:39], 0, v[12:13]
	global_load_dwordx4 v[58:61], v[58:59], off nt
	v_lshl_add_u64 v[54:55], v[38:39], 0, v[14:15]
	global_load_dwordx4 v[50:53], v[50:51], off nt
	v_lshl_add_u64 v[38:39], v[38:39], 0, v[18:19]
	global_load_dwordx4 v[54:57], v[54:55], off nt
	v_cmp_lt_i32_e64 s[0:1], v27, v26
	global_load_dwordx4 v[22:25], v[24:25], off offset:3072 nt
	s_waitcnt vmcnt(6)
	v_mov_b32_e32 v66, v36
	global_load_dwordx4 v[62:65], v[38:39], off nt
	v_lshlrev_b64 v[38:39], 11, v[20:21]
	v_lshl_add_u64 v[38:39], v[6:7], 0, v[38:39]
	v_cvt_pk_bf16_f32 v68, v34, v35
	v_cvt_pk_bf16_f32 v69, v36, v37
	s_waitcnt vmcnt(5)
	v_mov_b32_e32 v78, v47
	global_store_dwordx2 v[38:39], v[68:69], off
	s_waitcnt vmcnt(4)
	v_cvt_pk_bf16_f32 v68, v50, v51
	v_cvt_pk_bf16_f32 v69, v52, v53
	v_mov_b32_e32 v79, v59
	v_mov_b32_e32 v72, v42
	v_mov_b32_e32 v74, v43
	v_mov_b32_e32 v76, v46
	v_mov_b32_e32 v77, v58
	global_store_dwordx2 v[10:11], v[68:69], off
	v_cvt_pk_bf16_f32 v42, v42, v43
	v_cvt_pk_bf16_f32 v43, v44, v45
	v_pk_mul_f32 v[68:69], v[78:79], v[78:79]
	v_mov_b32_e32 v70, v44
	v_mov_b32_e32 v80, v48
	s_waitcnt vmcnt(4)
	v_mov_b32_e32 v71, v56
	v_mov_b32_e32 v81, v60
	global_store_dwordx2 v[38:39], v[42:43], off offset:512
	v_cvt_pk_bf16_f32 v42, v54, v55
	v_cvt_pk_bf16_f32 v43, v56, v57
	v_mov_b32_e32 v56, v45
	v_pk_fma_f32 v[44:45], v[76:77], v[76:77], v[68:69]
	v_mov_b32_e32 v36, v35
	v_mov_b32_e32 v67, v52
	v_mov_b32_e32 v52, v37
	v_mov_b32_e32 v37, v51
	v_mov_b32_e32 v75, v55
	global_store_dwordx2 v[10:11], v[42:43], off offset:512
	v_pk_fma_f32 v[42:43], v[80:81], v[80:81], v[44:45]
	v_cvt_pk_bf16_f32 v44, v46, v47
	v_cvt_pk_bf16_f32 v45, v48, v49
	v_mov_b32_e32 v35, v50
	v_mov_b32_e32 v73, v54
	v_pk_mul_f32 v[36:37], v[36:37], v[36:37]
	v_pk_mul_f32 v[50:51], v[74:75], v[74:75]
	global_store_dwordx2 v[38:39], v[44:45], off offset:1024
	v_cvt_pk_bf16_f32 v44, v58, v59
	v_cvt_pk_bf16_f32 v45, v60, v61
	v_pk_fma_f32 v[34:35], v[34:35], v[34:35], v[36:37]
	v_pk_fma_f32 v[36:37], v[72:73], v[72:73], v[50:51]
	global_store_dwordx2 v[10:11], v[44:45], off offset:1024
	s_waitcnt vmcnt(7)
	v_cvt_pk_bf16_f32 v44, v22, v23
	v_cvt_pk_bf16_f32 v45, v24, v25
	global_store_dwordx2 v[38:39], v[44:45], off offset:1536
	s_waitcnt vmcnt(7)
	v_cvt_pk_bf16_f32 v38, v62, v63
	v_mov_b32_e32 v82, v22
	v_pk_fma_f32 v[34:35], v[66:67], v[66:67], v[34:35]
	v_pk_fma_f32 v[36:37], v[70:71], v[70:71], v[36:37]
	v_mov_b32_e32 v84, v24
	v_pk_fma_f32 v[34:35], v[52:53], v[52:53], v[34:35]
	v_pk_fma_f32 v[36:37], v[56:57], v[56:57], v[36:37]
	v_mov_b32_e32 v60, v49
	v_pk_add_f32 v[34:35], v[34:35], v[36:37]
	v_pk_fma_f32 v[36:37], v[60:61], v[60:61], v[42:43]
	v_cvt_pk_bf16_f32 v39, v64, v65
	v_cndmask_b32_e64 v4, v1, v27, s[0:1]
	v_pk_add_f32 v[34:35], v[34:35], v[36:37]
	v_lshlrev_b32_e32 v4, 2, v4
	v_cmp_lt_i32_e64 s[0:1], v28, v26
	global_store_dwordx2 v[10:11], v[38:39], off offset:1536
	v_mov_b32_e32 v83, v62
	v_mov_b32_e32 v62, v23
	v_pk_mul_f32 v[22:23], v[62:63], v[62:63]
	v_mov_b32_e32 v85, v64
	v_pk_fma_f32 v[22:23], v[82:83], v[82:83], v[22:23]
	v_mov_b32_e32 v64, v25
	v_pk_fma_f32 v[22:23], v[84:85], v[84:85], v[22:23]
	s_nop 0
	v_pk_fma_f32 v[22:23], v[64:65], v[64:65], v[22:23]
	s_nop 0
	v_pk_add_f32 v[22:23], v[34:35], v[22:23]
	s_nop 1
	v_add_f32_dpp v22, v22, v22 quad_perm:[1,0,3,2] row_mask:0xf bank_mask:0xf
	v_add_f32_dpp v23, v23, v23 quad_perm:[1,0,3,2] row_mask:0xf bank_mask:0xf
	s_nop 1
	v_add_f32_dpp v22, v22, v22 quad_perm:[2,3,0,1] row_mask:0xf bank_mask:0xf
	v_add_f32_dpp v23, v23, v23 quad_perm:[2,3,0,1] row_mask:0xf bank_mask:0xf
	s_nop 1
	v_add_f32_dpp v22, v22, v22 row_half_mirror row_mask:0xf bank_mask:0xf
	v_add_f32_dpp v23, v23, v23 row_half_mirror row_mask:0xf bank_mask:0xf
	s_nop 1
	v_add_f32_dpp v22, v22, v22 row_mirror row_mask:0xf bank_mask:0xf
	v_add_f32_dpp v23, v23, v23 row_mirror row_mask:0xf bank_mask:0xf
	s_nop 1
	v_add_f32_dpp v22, v22, v22 row_bcast:15 row_mask:0xa bank_mask:0xf
	v_add_f32_dpp v23, v23, v23 row_bcast:15 row_mask:0xa bank_mask:0xf
	s_nop 1
	v_add_f32_dpp v22, v22, v22 row_bcast:31 row_mask:0xc bank_mask:0xf
	v_add_f32_dpp v23, v23, v23 row_bcast:31 row_mask:0xc bank_mask:0xf
	s_nop 1
	v_readlane_b32 s0, v22, 63
	v_readlane_b32 s1, v23, 63
	v_mov_b32_e32 v24, 0
	v_mov_b32_e32 v25, 0
	v_mov_b32_e32 v22, s0
	v_mov_b32_e32 v23, s1
	s_and_saveexec_b64 s[0:1], vcc
	s_cbranch_execz .LBB0_200
	v_readlane_b32 s28, v244, 0
	v_readlane_b32 s29, v244, 1
	s_waitcnt lgkmcnt(0)
	v_pk_add_f32 v[22:23], v[22:23], v[24:25]
	v_readlane_b32 s30, v244, 2
	v_lshl_add_u64 v[20:21], v[20:21], 2, s[28:29]
	v_readlane_b32 s31, v244, 3
	global_store_dwordx2 v[20:21], v[22:23], off
	s_branch .LBB0_200

.LBB0_779:
	v_mov_b32_e32 v43, v0
	s_ashr_i32 s5, s3, 31
	v_ashrrev_i32_e32 v44, 7, v43
	s_waitcnt vmcnt(2)
	v_add_u32_e32 v164, s2, v44
	v_ashrrev_i32_e32 v165, 31, v164
	v_and_b32_e32 v168, 31, v43
	s_waitcnt vmcnt(0)
	v_lshlrev_b64 v[2:3], 15, v[164:165]
	v_bfe_u32 v169, v43, 5, 1
	v_lshl_add_u64 v[2:3], s[56:57], 0, v[2:3]
	v_and_b32_e32 v18, 63, v43
	v_lshlrev_b32_e32 v18, 4, v18
	v_lshlrev_b32_e32 v154, 4, v169
	v_add_u32_e32 v18, 0x1000, v18
	v_add_co_u32_e32 v18, vcc, v2, v18
	s_nop 1
	v_addc_co_u32_e32 v19, vcc, 0, v3, vcc
	v_add_co_u32_e32 v20, vcc, s14, v18
	v_ashrrev_i32_e32 v45, 2, v43
	s_nop 0
	v_addc_co_u32_e32 v21, vcc, 0, v19, vcc
	v_add_co_u32_e32 v22, vcc, s17, v18
	global_load_dwordx4 v[2:5], v[18:19], off offset:-4096
	global_load_dwordx4 v[6:9], v[20:21], off offset:-4096
	v_addc_co_u32_e32 v23, vcc, 0, v19, vcc
	v_add_co_u32_e32 v24, vcc, s30, v18
	global_load_dwordx4 v[10:13], v[22:23], off offset:-4096
	s_nop 0
	v_addc_co_u32_e32 v25, vcc, 0, v19, vcc
	global_load_dwordx4 v[14:17], v[24:25], off offset:-4096
	global_load_dwordx4 v[138:141], v[18:19], off offset:-3072
	global_load_dwordx4 v[142:145], v[20:21], off offset:-3072
	global_load_dwordx4 v[146:149], v[22:23], off offset:-3072
	global_load_dwordx4 v[150:153], v[24:25], off offset:-3072
	global_load_dwordx4 v[126:129], v[20:21], off offset:-2048
	global_load_dwordx4 v[130:133], v[22:23], off offset:-2048
	global_load_dwordx4 v[134:137], v[24:25], off offset:-2048
	global_load_dwordx4 v[114:117], v[20:21], off offset:-1024
	global_load_dwordx4 v[118:121], v[22:23], off offset:-1024
	global_load_dwordx4 v[122:125], v[24:25], off offset:-1024
	global_load_dwordx4 v[106:109], v[22:23], off
	global_load_dwordx4 v[110:113], v[24:25], off
	global_load_dwordx4 v[98:101], v[22:23], off offset:1024
	global_load_dwordx4 v[102:105], v[24:25], off offset:1024
	global_load_dwordx4 v[94:97], v[24:25], off offset:2048
	global_load_dwordx4 v[90:93], v[24:25], off offset:3072
	v_add_u32_e32 v18, s3, v45
	v_ashrrev_i32_e32 v19, 31, v18
	v_lshlrev_b32_e32 v20, 6, v43
	v_lshlrev_b64 v[18:19], 12, v[18:19]
	v_and_b32_e32 v46, 0xc0, v20
	v_lshl_add_u64 v[18:19], s[60:61], 0, v[18:19]
	v_lshlrev_b32_e32 v20, 1, v46
	v_mov_b32_e32 v21, v155
	v_lshl_add_u64 v[34:35], v[18:19], 0, v[20:21]
	global_load_dwordx4 v[18:21], v[34:35], off offset:3632
	global_load_dwordx4 v[22:25], v[34:35], off offset:3616
	global_load_dwordx4 v[26:29], v[34:35], off offset:3600
	global_load_dwordx4 v[30:33], v[34:35], off offset:3584
	global_load_dwordx4 v[36:39], v[34:35], off offset:3680
	global_load_dwordx4 v[202:205], v[34:35], off offset:3664
	global_load_dwordx4 v[48:51], v[34:35], off offset:3648
	global_load_dwordx4 v[206:209], v[34:35], off offset:3696
	v_lshrrev_b32_e32 v42, 5, v43
	s_add_i32 s4, s4, s46
	s_waitcnt vmcnt(7)
	v_lshlrev_b32_e32 v178, 16, v18
	s_waitcnt vmcnt(6)
	v_lshlrev_b32_e32 v186, 16, v22
	s_waitcnt vmcnt(5)
	v_lshlrev_b32_e32 v194, 16, v26
	s_waitcnt vmcnt(4)
	v_lshlrev_b32_e32 v200, 16, v30
	v_and_b32_e32 v199, 0xffff0000, v30
	v_add_f32_e32 v30, 0, v200
	v_lshlrev_b32_e32 v198, 16, v31
	v_add_f32_e32 v30, v30, v199
	v_and_b32_e32 v197, 0xffff0000, v31
	v_mul_f32_e32 v31, v199, v199
	v_add_f32_e32 v30, v30, v198
	v_lshlrev_b32_e32 v196, 16, v32
	v_fmac_f32_e32 v31, v200, v200
	v_add_f32_e32 v30, v30, v197
	v_and_b32_e32 v195, 0xffff0000, v32
	v_fmac_f32_e32 v31, v198, v198
	v_add_f32_e32 v30, v30, v196
	v_lshlrev_b32_e32 v193, 16, v33
	v_fmac_f32_e32 v31, v197, v197
	v_add_f32_e32 v30, v30, v195
	v_and_b32_e32 v191, 0xffff0000, v33
	v_fmac_f32_e32 v31, v196, v196
	v_add_f32_e32 v30, v30, v193
	v_fmac_f32_e32 v31, v195, v195
	v_add_f32_e32 v30, v30, v191
	v_fmac_f32_e32 v31, v193, v193
	v_and_b32_e32 v192, 0xffff0000, v26
	v_add_f32_e32 v26, v30, v194
	v_fmac_f32_e32 v31, v191, v191
	v_lshlrev_b32_e32 v190, 16, v27
	v_add_f32_e32 v26, v26, v192
	v_and_b32_e32 v189, 0xffff0000, v27
	v_fmac_f32_e32 v31, v194, v194
	v_add_f32_e32 v26, v26, v190
	v_lshlrev_b32_e32 v188, 16, v28
	v_fmac_f32_e32 v31, v192, v192
	v_add_f32_e32 v26, v26, v189
	v_and_b32_e32 v187, 0xffff0000, v28
	v_fmac_f32_e32 v31, v190, v190
	v_add_f32_e32 v26, v26, v188
	v_lshlrev_b32_e32 v184, 16, v29
	v_fmac_f32_e32 v31, v189, v189
	v_add_f32_e32 v26, v26, v187
	v_and_b32_e32 v182, 0xffff0000, v29
	v_fmac_f32_e32 v31, v188, v188
	v_add_f32_e32 v26, v26, v184
	v_fmac_f32_e32 v31, v187, v187
	v_add_f32_e32 v26, v26, v182
	v_fmac_f32_e32 v31, v184, v184
	v_and_b32_e32 v185, 0xffff0000, v22
	v_add_f32_e32 v22, v26, v186
	v_fmac_f32_e32 v31, v182, v182
	v_lshlrev_b32_e32 v183, 16, v23
	v_add_f32_e32 v22, v22, v185
	v_and_b32_e32 v179, 0xffff0000, v23
	v_fmac_f32_e32 v31, v186, v186
	v_add_f32_e32 v22, v22, v183
	v_lshlrev_b32_e32 v177, 16, v24
	v_fmac_f32_e32 v31, v185, v185
	v_add_f32_e32 v22, v22, v179
	v_and_b32_e32 v175, 0xffff0000, v24
	v_fmac_f32_e32 v31, v183, v183
	v_add_f32_e32 v22, v22, v177
	v_lshlrev_b32_e32 v173, 16, v25
	v_fmac_f32_e32 v31, v179, v179
	v_add_f32_e32 v22, v22, v175
	v_and_b32_e32 v171, 0xffff0000, v25
	v_fmac_f32_e32 v31, v177, v177
	v_add_f32_e32 v22, v22, v173
	v_fmac_f32_e32 v31, v175, v175
	v_add_f32_e32 v22, v22, v171
	v_fmac_f32_e32 v31, v173, v173
	v_and_b32_e32 v176, 0xffff0000, v18
	v_add_f32_e32 v18, v22, v178
	v_fmac_f32_e32 v31, v171, v171
	v_lshlrev_b32_e32 v174, 16, v19
	v_add_f32_e32 v18, v18, v176
	v_and_b32_e32 v172, 0xffff0000, v19
	v_fmac_f32_e32 v31, v178, v178
	v_add_f32_e32 v18, v18, v174
	v_lshlrev_b32_e32 v167, 16, v20
	v_fmac_f32_e32 v31, v176, v176
	v_add_f32_e32 v18, v18, v172
	v_and_b32_e32 v165, 0xffff0000, v20
	v_fmac_f32_e32 v31, v174, v174
	v_add_f32_e32 v18, v18, v167
	v_lshlrev_b32_e32 v64, 16, v21
	v_fmac_f32_e32 v31, v172, v172
	v_add_f32_e32 v18, v18, v165
	v_and_b32_e32 v62, 0xffff0000, v21
	v_fmac_f32_e32 v31, v167, v167
	v_add_f32_e32 v18, v18, v64
	v_fmac_f32_e32 v31, v165, v165
	v_add_f32_e32 v18, v18, v62
	s_waitcnt vmcnt(1)
	v_lshlrev_b32_e32 v170, 16, v48
	v_fmac_f32_e32 v31, v64, v64
	v_and_b32_e32 v166, 0xffff0000, v48
	v_add_f32_e32 v18, v18, v170
	v_fmac_f32_e32 v31, v62, v62
	v_lshlrev_b32_e32 v65, 16, v49
	v_add_f32_e32 v18, v18, v166
	v_and_b32_e32 v63, 0xffff0000, v49
	v_fmac_f32_e32 v31, v170, v170
	v_add_f32_e32 v18, v18, v65
	v_lshlrev_b32_e32 v60, 16, v50
	v_fmac_f32_e32 v31, v166, v166
	v_add_f32_e32 v18, v18, v63
	v_and_b32_e32 v59, 0xffff0000, v50
	v_fmac_f32_e32 v31, v65, v65
	v_add_f32_e32 v18, v18, v60
	v_lshlrev_b32_e32 v57, 16, v51
	v_fmac_f32_e32 v31, v63, v63
	v_add_f32_e32 v18, v18, v59
	v_and_b32_e32 v55, 0xffff0000, v51
	v_fmac_f32_e32 v31, v60, v60
	v_add_f32_e32 v18, v18, v57
	v_fmac_f32_e32 v31, v59, v59
	v_add_f32_e32 v18, v18, v55
	v_lshlrev_b32_e32 v61, 16, v202
	v_fmac_f32_e32 v31, v57, v57
	v_and_b32_e32 v58, 0xffff0000, v202
	v_add_f32_e32 v18, v18, v61
	v_fmac_f32_e32 v31, v55, v55
	v_lshlrev_b32_e32 v56, 16, v203
	v_add_f32_e32 v18, v18, v58
	v_and_b32_e32 v54, 0xffff0000, v203
	v_fmac_f32_e32 v31, v61, v61
	v_add_f32_e32 v18, v18, v56
	v_lshlrev_b32_e32 v53, 16, v204
	v_fmac_f32_e32 v31, v58, v58
	v_add_f32_e32 v18, v18, v54
	v_and_b32_e32 v51, 0xffff0000, v204
	v_fmac_f32_e32 v31, v56, v56
	v_add_f32_e32 v18, v18, v53
	v_lshlrev_b32_e32 v49, 16, v205
	v_fmac_f32_e32 v31, v54, v54
	v_add_f32_e32 v18, v18, v51
	v_and_b32_e32 v47, 0xffff0000, v205
	v_fmac_f32_e32 v31, v53, v53
	v_add_f32_e32 v18, v18, v49
	v_fmac_f32_e32 v31, v51, v51
	v_add_f32_e32 v18, v18, v47
	v_lshlrev_b32_e32 v52, 16, v36
	v_fmac_f32_e32 v31, v49, v49
	v_and_b32_e32 v50, 0xffff0000, v36
	v_add_f32_e32 v18, v18, v52
	v_fmac_f32_e32 v31, v47, v47
	v_lshlrev_b32_e32 v48, 16, v37
	v_add_f32_e32 v18, v18, v50
	v_fmac_f32_e32 v31, v52, v52
	v_add_f32_e32 v18, v18, v48
	v_and_b32_e32 v37, 0xffff0000, v37
	v_fmac_f32_e32 v31, v50, v50
	v_lshlrev_b32_e32 v34, 16, v38
	v_mov_b32_e32 v35, v37
	v_add_f32_e32 v20, v18, v37
	v_fmac_f32_e32 v31, v48, v48
	v_and_b32_e32 v24, 0xffff0000, v38
	v_pk_mul_f32 v[18:19], v[34:35], v[34:35]
	v_add_f32_e32 v20, v20, v34
	v_lshlrev_b32_e32 v25, 16, v39
	v_add_f32_e32 v19, v19, v31
	v_add_f32_e32 v20, v20, v24
	v_add_f32_e32 v21, v18, v19
	v_pk_mul_f32 v[18:19], v[24:25], v[24:25]
	v_add_f32_e32 v20, v20, v25
	v_and_b32_e32 v33, 0xffff0000, v39
	v_add_f32_e32 v18, v18, v21
	s_waitcnt vmcnt(0)
	v_lshlrev_b32_e32 v28, 16, v206
	v_mov_b32_e32 v29, v33
	v_add_f32_e32 v20, v20, v33
	v_add_f32_e32 v21, v19, v18
	v_and_b32_e32 v22, 0xffff0000, v206
	v_pk_mul_f32 v[18:19], v[28:29], v[28:29]
	v_add_f32_e32 v20, v20, v28
	v_lshlrev_b32_e32 v23, 16, v207
	v_add_f32_e32 v19, v19, v21
	v_add_f32_e32 v20, v20, v22
	v_add_f32_e32 v21, v18, v19
	v_pk_mul_f32 v[18:19], v[22:23], v[22:23]
	v_add_f32_e32 v29, v20, v23
	v_and_b32_e32 v31, 0xffff0000, v207
	v_add_f32_e32 v18, v18, v21
	v_lshlrev_b32_e32 v26, 16, v208
	v_mov_b32_e32 v27, v31
	v_add_f32_e32 v29, v29, v31
	v_and_b32_e32 v36, s0, v38
	v_add_f32_e32 v18, v19, v18
	v_and_b32_e32 v20, 0xffff0000, v208
	v_pk_mul_f32 v[38:39], v[26:27], v[26:27]
	v_add_f32_e32 v27, v29, v26
	v_lshlrev_b32_e32 v21, 16, v209
	v_add_f32_e32 v18, v39, v18
	v_add_f32_e32 v27, v27, v20
	v_and_b32_e32 v29, 64, v181
	v_add_f32_e32 v18, v38, v18
	v_pk_mul_f32 v[40:41], v[20:21], v[20:21]
	v_add_f32_e32 v39, v27, v21
	v_xor_b32_e32 v27, 1, v181
	v_add_u32_e32 v29, 64, v29
	v_and_b32_e32 v19, 0xffff0000, v209
	v_add_f32_e32 v18, v40, v18
	v_cmp_lt_i32_e32 vcc, v27, v29
	v_add_f32_e32 v18, v41, v18
	v_mul_f32_e32 v38, v19, v19
	v_cndmask_b32_e32 v27, v181, v27, vcc
	v_lshlrev_b32_e32 v27, 2, v27
	v_pk_add_f32 v[38:39], v[38:39], v[18:19]
	s_nop 1
	v_mov_b32_dpp v41, v39 quad_perm:[1,0,3,2] row_mask:0xf bank_mask:0xf
	v_mov_b32_dpp v40, v38 quad_perm:[1,0,3,2] row_mask:0xf bank_mask:0xf
	v_xor_b32_e32 v35, 2, v181
	v_cmp_lt_i32_e32 vcc, v35, v29
	v_and_b32_e32 v30, s0, v206
	v_mov_b32_e32 v32, v36
	v_cndmask_b32_e32 v29, v181, v35, vcc
	v_lshlrev_b32_e32 v29, 2, v29
	s_waitcnt lgkmcnt(0)
	v_pk_add_f32 v[38:39], v[38:39], v[40:41]
	s_nop 1
	v_mov_b32_dpp v41, v39 quad_perm:[2,3,0,1] row_mask:0xf bank_mask:0xf
	v_mov_b32_dpp v40, v38 quad_perm:[2,3,0,1] row_mask:0xf bank_mask:0xf
	s_waitcnt lgkmcnt(0)
	v_pk_add_f32 v[40:41], v[38:39], v[40:41]
	s_nop 0
	v_pk_mul_f32 v[38:39], v[40:41], s[22:23] op_sel_hi:[1,0]
	v_pk_fma_f32 v[36:37], v[40:41], s[22:23], v[36:37] op_sel_hi:[1,0,1] neg_lo:[1,0,0] neg_hi:[1,0,0]
	v_fma_f32 v18, -v39, v39, v38
	v_max_f32_e32 v18, 0, v18
	v_add_f32_e32 v18, 0x358637bd, v18
	v_cmp_gt_f32_e32 vcc, s33, v18
	v_mul_f32_e32 v27, 0x4b800000, v18
	v_sub_f32_e32 v29, v200, v39
	v_cndmask_b32_e32 v18, v18, v27, vcc
	v_rsq_f32_e32 v18, v18
	v_sub_f32_e32 v19, v19, v39
	v_mul_f32_e32 v27, 0x45800000, v18
	v_cndmask_b32_e32 v18, v18, v27, vcc
	v_mul_f32_e32 v29, v29, v18
	v_lshlrev_b32_e32 v27, 1, v45
	v_bfe_u32 v35, v29, 16, 1
	v_ashrrev_i32_e32 v45, 1, v43
	v_and_b32_e32 v27, 14, v27
	v_add3_u32 v29, v29, v35, s15
	v_lshl_add_u32 v35, v46, 8, 32
	v_and_b32_e32 v46, -16, v45
	v_add3_u32 v200, v35, v46, v27
	ds_write_b16_d16_hi v200, v29 offset:55296
	v_mul_f32_e64 v215, -v39, v18
	v_fma_f32 v29, v199, v18, v215
	v_cvt_pk_bf16_f32 v29, v29, v29
	v_bitop3_b32 v199, v45, 16, -16 bitop3:0x6c
	v_add3_u32 v201, v35, v199, v27
	ds_write_b16 v201, v29 offset:55552
	v_fma_f32 v29, v198, v18, v215
	v_cvt_pk_bf16_f32 v29, v29, v29
	v_bitop3_b32 v198, v45, 32, -16 bitop3:0x6c
	v_add3_u32 v202, v35, v198, v27
	ds_write_b16 v202, v29 offset:55808
	v_fma_f32 v29, v197, v18, v215
	v_cvt_pk_bf16_f32 v29, v29, v29
	v_bitop3_b32 v197, v45, 48, -16 bitop3:0x6c
	v_add3_u32 v203, v35, v197, v27
	ds_write_b16 v203, v29 offset:56064
	v_fma_f32 v29, v196, v18, v215
	v_cvt_pk_bf16_f32 v29, v29, v29
	v_bitop3_b32 v196, v45, 64, -16 bitop3:0x6c
	v_add3_u32 v204, v35, v196, v27
	ds_write_b16 v204, v29 offset:56320
	v_fma_f32 v29, v195, v18, v215
	v_cvt_pk_bf16_f32 v29, v29, v29
	v_bitop3_b32 v195, v45, s34, -16 bitop3:0x6c
	v_add3_u32 v205, v35, v195, v27
	ds_write_b16 v205, v29 offset:56576
	v_fma_f32 v29, v193, v18, v215
	v_cvt_pk_bf16_f32 v29, v29, v29
	v_bitop3_b32 v193, v45, s31, -16 bitop3:0x6c
	v_add3_u32 v206, v35, v193, v27
	ds_write_b16 v206, v29 offset:56832
	v_fma_f32 v29, v191, v18, v215
	v_cvt_pk_bf16_f32 v29, v29, v29
	v_bitop3_b32 v191, v45, s13, -16 bitop3:0x6c
	v_add3_u32 v207, v35, v191, v27
	ds_write_b16 v207, v29 offset:57088
	v_fma_f32 v29, v194, v18, v215
	v_cvt_pk_bf16_f32 v29, v29, v29
	v_bitop3_b32 v194, v45, s12, -16 bitop3:0x6c
	v_add3_u32 v208, v35, v194, v27
	ds_write_b16 v208, v29 offset:57344
	v_fma_f32 v29, v192, v18, v215
	v_cvt_pk_bf16_f32 v29, v29, v29
	v_bitop3_b32 v192, v45, s35, -16 bitop3:0x6c
	v_add3_u32 v209, v35, v192, v27
	ds_write_b16 v209, v29 offset:57600
	v_fma_f32 v29, v190, v18, v215
	v_cvt_pk_bf16_f32 v29, v29, v29
	v_bitop3_b32 v190, v45, s36, -16 bitop3:0x6c
	v_add3_u32 v210, v35, v190, v27
	ds_write_b16 v210, v29 offset:57856
	v_fma_f32 v29, v189, v18, v215
	v_cvt_pk_bf16_f32 v29, v29, v29
	v_bitop3_b32 v189, v45, s37, -16 bitop3:0x6c
	v_add3_u32 v211, v35, v189, v27
	ds_write_b16 v211, v29 offset:58112
	v_fma_f32 v29, v188, v18, v215
	v_cvt_pk_bf16_f32 v29, v29, v29
	v_bitop3_b32 v188, v45, s16, -16 bitop3:0x6c
	v_add3_u32 v212, v35, v188, v27
	ds_write_b16 v212, v29 offset:58368
	v_fma_f32 v29, v187, v18, v215
	v_cvt_pk_bf16_f32 v29, v29, v29
	v_bitop3_b32 v187, v45, s42, -16 bitop3:0x6c
	v_add3_u32 v213, v35, v187, v27
	ds_write_b16 v213, v29 offset:58624
	v_fma_f32 v29, v184, v18, v215
	v_cvt_pk_bf16_f32 v29, v29, v29
	v_bitop3_b32 v184, v45, s43, -16 bitop3:0x6c
	v_add3_u32 v214, v35, v184, v27
	ds_write_b16 v214, v29 offset:58880
	v_sub_f32_e32 v29, v182, v39
	v_mul_f32_e32 v29, v29, v18
	v_bfe_u32 v182, v29, 16, 1
	v_bitop3_b32 v45, v45, s94, -16 bitop3:0x6c
	v_add_u32_e32 v38, 0xd800, v35
	v_add3_u32 v29, v29, v182, s15
	v_add3_u32 v35, v35, v45, v27
	ds_write_b16_d16_hi v35, v29 offset:59136
	v_fma_f32 v29, v186, v18, v215
	v_cvt_pk_bf16_f32 v29, v29, v29
	ds_write_b16 v200, v29 offset:59392
	v_fma_f32 v29, v185, v18, v215
	v_cvt_pk_bf16_f32 v29, v29, v29
	ds_write_b16 v201, v29 offset:59648
	v_fma_f32 v29, v183, v18, v215
	v_cvt_pk_bf16_f32 v29, v29, v29
	ds_write_b16 v202, v29 offset:59904
	v_fma_f32 v29, v179, v18, v215
	v_cvt_pk_bf16_f32 v29, v29, v29
	ds_write_b16 v203, v29 offset:60160
	v_fma_f32 v29, v177, v18, v215
	v_cvt_pk_bf16_f32 v29, v29, v29
	ds_write_b16 v204, v29 offset:60416
	v_fma_f32 v29, v175, v18, v215
	v_cvt_pk_bf16_f32 v29, v29, v29
	ds_write_b16 v205, v29 offset:60672
	v_fma_f32 v29, v173, v18, v215
	v_cvt_pk_bf16_f32 v29, v29, v29
	ds_write_b16 v206, v29 offset:60928
	v_fma_f32 v29, v171, v18, v215
	v_cvt_pk_bf16_f32 v29, v29, v29
	ds_write_b16 v207, v29 offset:61184
	v_fma_f32 v29, v178, v18, v215
	v_cvt_pk_bf16_f32 v29, v29, v29
	ds_write_b16 v208, v29 offset:61440
	v_fma_f32 v29, v176, v18, v215
	v_cvt_pk_bf16_f32 v29, v29, v29
	ds_write_b16 v209, v29 offset:61696
	v_fma_f32 v29, v174, v18, v215
	v_cvt_pk_bf16_f32 v29, v29, v29
	ds_write_b16 v210, v29 offset:61952
	v_fma_f32 v29, v172, v18, v215
	v_cvt_pk_bf16_f32 v29, v29, v29
	ds_write_b16 v211, v29 offset:62208
	v_fma_f32 v29, v167, v18, v215
	v_cvt_pk_bf16_f32 v29, v29, v29
	ds_write_b16 v212, v29 offset:62464
	v_fma_f32 v29, v165, v18, v215
	v_cvt_pk_bf16_f32 v29, v29, v29
	ds_write_b16 v213, v29 offset:62720
	v_fma_f32 v29, v64, v18, v215
	v_cvt_pk_bf16_f32 v29, v29, v29
	ds_write_b16 v214, v29 offset:62976
	v_fma_f32 v29, v62, v18, v215
	v_cvt_pk_bf16_f32 v29, v29, v29
	ds_write_b16 v35, v29 offset:63232
	v_fma_f32 v29, v170, v18, v215
	v_cvt_pk_bf16_f32 v29, v29, v29
	ds_write_b16 v200, v29 offset:63488
	v_fma_f32 v29, v166, v18, v215
	v_cvt_pk_bf16_f32 v29, v29, v29
	ds_write_b16 v201, v29 offset:63744
	v_fma_f32 v29, v65, v18, v215
	v_cvt_pk_bf16_f32 v29, v29, v29
	ds_write_b16 v202, v29 offset:64000
	v_fma_f32 v29, v63, v18, v215
	v_cvt_pk_bf16_f32 v29, v29, v29
	ds_write_b16 v203, v29 offset:64256
	v_fma_f32 v29, v60, v18, v215
	v_cvt_pk_bf16_f32 v29, v29, v29
	ds_write_b16 v204, v29 offset:64512
	v_fma_f32 v29, v59, v18, v215
	v_cvt_pk_bf16_f32 v29, v29, v29
	ds_write_b16 v205, v29 offset:64768
	v_fma_f32 v29, v57, v18, v215
	v_cvt_pk_bf16_f32 v29, v29, v29
	ds_write_b16 v206, v29 offset:65024
	v_fma_f32 v29, v55, v18, v215
	v_cvt_pk_bf16_f32 v29, v29, v29
	ds_write_b16 v207, v29 offset:65280
	v_fma_f32 v29, v61, v18, v215
	v_cvt_pk_bf16_f32 v29, v29, v29
	v_add3_u32 v35, v38, v194, v27
	ds_write_b16 v35, v29 offset:10240
	v_fma_f32 v29, v58, v18, v215
	v_cvt_pk_bf16_f32 v29, v29, v29
	v_add3_u32 v55, v38, v192, v27
	ds_write_b16 v55, v29 offset:10496
	v_fma_f32 v29, v56, v18, v215
	v_cvt_pk_bf16_f32 v29, v29, v29
	v_add3_u32 v56, v38, v190, v27
	ds_write_b16 v56, v29 offset:10752
	v_fma_f32 v29, v54, v18, v215
	v_cvt_pk_bf16_f32 v29, v29, v29
	v_add3_u32 v54, v38, v189, v27
	ds_write_b16 v54, v29 offset:11008
	v_fma_f32 v29, v53, v18, v215
	v_cvt_pk_bf16_f32 v29, v29, v29
	v_add3_u32 v53, v38, v188, v27
	ds_write_b16 v53, v29 offset:11264
	v_fma_f32 v29, v51, v18, v215
	v_cvt_pk_bf16_f32 v29, v29, v29
	v_add3_u32 v51, v38, v187, v27
	ds_write_b16 v51, v29 offset:11520
	v_fma_f32 v29, v49, v18, v215
	v_cvt_pk_bf16_f32 v29, v29, v29
	v_add3_u32 v49, v38, v184, v27
	ds_write_b16 v49, v29 offset:11776
	v_fma_f32 v29, v47, v18, v215
	v_cvt_pk_bf16_f32 v29, v29, v29
	v_add3_u32 v45, v38, v45, v27
	ds_write_b16 v45, v29 offset:12032
	v_fma_f32 v29, v52, v18, v215
	v_cvt_pk_bf16_f32 v29, v29, v29
	v_add3_u32 v46, v38, v46, v27
	ds_write_b16 v46, v29 offset:12288
	v_fma_f32 v29, v50, v18, v215
	v_cvt_pk_bf16_f32 v29, v29, v29
	v_add3_u32 v46, v38, v199, v27
	ds_write_b16 v46, v29 offset:12544
	v_fma_f32 v29, v48, v18, v215
	v_cvt_pk_bf16_f32 v29, v29, v29
	v_add3_u32 v46, v38, v198, v27
	ds_write_b16 v46, v29 offset:12800
	v_mul_f32_e32 v29, v37, v18
	v_bfe_u32 v36, v29, 16, 1
	v_add3_u32 v29, v29, v36, s15
	v_add3_u32 v36, v38, v197, v27
	ds_write_b16_d16_hi v36, v29 offset:13056
	v_fma_f32 v29, v34, v18, v215
	v_cvt_pk_bf16_f32 v29, v29, v29
	v_add3_u32 v34, v38, v196, v27
	ds_write_b16 v34, v29 offset:13312
	v_sub_f32_e32 v29, v24, v39
	v_pk_fma_f32 v[24:25], v[40:41], s[22:23], v[24:25] op_sel_hi:[1,0,1] neg_lo:[1,0,0] neg_hi:[1,0,0]
	v_mul_f32_e32 v29, v29, v18
	v_mul_f32_e32 v24, v25, v18
	v_bfe_u32 v34, v29, 16, 1
	v_bfe_u32 v25, v24, 16, 1
	v_add3_u32 v29, v29, v34, s15
	v_add3_u32 v34, v38, v195, v27
	v_add3_u32 v24, v24, v25, s15
	v_add3_u32 v25, v38, v193, v27
	ds_write_b16_d16_hi v34, v29 offset:13568
	ds_write_b16_d16_hi v25, v24 offset:13824
	v_pk_fma_f32 v[24:25], v[40:41], s[22:23], v[32:33] op_sel_hi:[1,0,1] neg_lo:[1,0,0] neg_hi:[1,0,0]
	v_and_b32_e32 v167, 15, v43
	v_mul_f32_e32 v24, v25, v18
	v_bfe_u32 v25, v24, 16, 1
	v_add3_u32 v24, v24, v25, s15
	v_add3_u32 v25, v38, v191, v27
	ds_write_b16_d16_hi v25, v24 offset:14080
	v_fma_f32 v24, v28, v18, v215
	v_cvt_pk_bf16_f32 v24, v24, v24
	ds_write_b16 v35, v24 offset:14336
	v_sub_f32_e32 v24, v22, v39
	v_pk_fma_f32 v[22:23], v[40:41], s[22:23], v[22:23] op_sel_hi:[1,0,1] neg_lo:[1,0,0] neg_hi:[1,0,0]
	v_mul_f32_e32 v24, v24, v18
	v_mul_f32_e32 v22, v23, v18
	v_bfe_u32 v25, v24, 16, 1
	v_bfe_u32 v23, v22, 16, 1
	v_add3_u32 v24, v24, v25, s15
	v_add3_u32 v22, v22, v23, s15
	ds_write_b16_d16_hi v55, v24 offset:14592
	ds_write_b16_d16_hi v56, v22 offset:14848
	v_pk_fma_f32 v[22:23], v[40:41], s[22:23], v[30:31] op_sel_hi:[1,0,1] neg_lo:[1,0,0] neg_hi:[1,0,0]
	s_nop 0
	v_mul_f32_e32 v22, v23, v18
	v_bfe_u32 v23, v22, 16, 1
	v_add3_u32 v22, v22, v23, s15
	ds_write_b16_d16_hi v54, v22 offset:15104
	v_fma_f32 v22, v26, v18, v215
	v_cvt_pk_bf16_f32 v22, v22, v22
	ds_write_b16 v53, v22 offset:15360
	v_sub_f32_e32 v22, v20, v39
	v_pk_fma_f32 v[20:21], v[40:41], s[22:23], v[20:21] op_sel_hi:[1,0,1] neg_lo:[1,0,0] neg_hi:[1,0,0]
	v_mul_f32_e32 v22, v22, v18
	v_mul_f32_e32 v20, v21, v18
	v_mul_f32_e32 v18, v19, v18
	v_bfe_u32 v23, v22, 16, 1
	v_bfe_u32 v21, v20, 16, 1
	v_bfe_u32 v19, v18, 16, 1
	v_add3_u32 v22, v22, v23, s15
	v_add3_u32 v20, v20, v21, s15
	v_add3_u32 v18, v18, v19, s15
	ds_write_b16_d16_hi v51, v22 offset:15616
	ds_write_b16_d16_hi v49, v20 offset:15872
	ds_write_b16_d16_hi v45, v18 offset:16128
	v_lshrrev_b32_e32 v18, 1, v43
	v_and_b32_e32 v18, 32, v18
	v_lshl_or_b32 v166, v44, 6, v18
	v_or_b32_e32 v18, v166, v168
	v_lshl_add_u32 v165, v18, 8, 32
	v_bitop3_b32 v18, v42, v167, 1 bitop3:0x6c
	v_lshl_add_u32 v18, v18, 4, v165
	v_and_b32_e32 v215, 31, v0
	v_add_u32_e32 v215, s3, v215
	v_lshlrev_b32_e32 v215, 12, v215
	v_and_b32_e32 v245, 0x1c0, v0
	v_add_u32_e32 v215, v215, v245
	v_bfe_u32 v245, v0, 5, 1
	v_lshl_add_u32 v245, v245, 3, v215
	v_bfe_u32 v215, v0, 5, 1
	v_lshl_add_u32 v215, v215, 3, v245
	global_load_dwordx4 v[216:219], v215, s[60:61] offset:3072
	global_load_dwordx4 v[220:223], v215, s[60:61] offset:3104
	s_add_u32 s98, s60, 0x20000
	s_addc_u32 s99, s61, 0
	global_load_dwordx4 v[224:227], v215, s[98:99] offset:3072
	global_load_dwordx4 v[228:231], v215, s[98:99] offset:3104
	s_add_u32 s100, s60, 0x40000
	s_addc_u32 s101, s61, 0
	global_load_dwordx4 v[232:235], v215, s[100:101] offset:3072
	global_load_dwordx4 v[236:239], v215, s[100:101] offset:3104
	s_add_u32 s98, s60, 0x60000
	s_addc_u32 s99, s61, 0
	global_load_dwordx4 v[252:255], v215, s[98:99] offset:3072
	global_load_dwordx2 v[240:241], v245, s[98:99] offset:3104
	global_load_dwordx2 v[246:247], v245, s[98:99] offset:3120
	s_waitcnt lgkmcnt(0)
	s_barrier
	ds_read_b128 v[170:173], v18 offset:55296
	s_waitcnt lgkmcnt(0)
	v_mfma_f32_32x32x16_bf16 v[50:65], v[170:173], v[2:5], 0
	v_mfma_f32_32x32x16_bf16 v[34:49], v[170:173], v[6:9], 0
	v_mfma_f32_32x32x16_bf16 v[18:33], v[170:173], v[10:13], 0
	v_mfma_f32_32x32x16_bf16 v[2:17], v[170:173], v[14:17], 0
	v_bitop3_b32 v170, v169, v167, 2 bitop3:0x36
	v_lshl_add_u32 v170, v170, 4, v165
	ds_read_b128 v[170:173], v170 offset:55296
	s_waitcnt lgkmcnt(0)
	v_mfma_f32_32x32x16_bf16 v[50:65], v[170:173], v[138:141], v[50:65]
	v_bitop3_b32 v138, v169, v167, 4 bitop3:0x36
	v_lshl_add_u32 v138, v138, 4, v165
	ds_read_b128 v[138:141], v138 offset:55296
	v_mfma_f32_32x32x16_bf16 v[34:49], v[170:173], v[142:145], v[34:49]
	v_mfma_f32_32x32x16_bf16 v[18:33], v[170:173], v[146:149], v[18:33]
	s_waitcnt lgkmcnt(0)
	v_mfma_f32_32x32x16_bf16 v[34:49], v[138:141], v[126:129], v[34:49]
	v_bitop3_b32 v126, v169, v167, 6 bitop3:0x36
	v_lshl_add_u32 v126, v126, 4, v165
	ds_read_b128 v[126:129], v126 offset:55296
	v_mfma_f32_32x32x16_bf16 v[2:17], v[170:173], v[150:153], v[2:17]
	v_mfma_f32_32x32x16_bf16 v[18:33], v[138:141], v[130:133], v[18:33]
	s_waitcnt lgkmcnt(0)
	v_mfma_f32_32x32x16_bf16 v[34:49], v[126:129], v[114:117], v[34:49]
	v_bitop3_b32 v114, v169, v167, 8 bitop3:0x36
	v_lshl_add_u32 v114, v114, 4, v165
	ds_read_b128 v[114:117], v114 offset:55296
	v_mfma_f32_32x32x16_bf16 v[2:17], v[138:141], v[134:137], v[2:17]
	v_mfma_f32_32x32x16_bf16 v[18:33], v[126:129], v[118:121], v[18:33]
	v_mfma_f32_32x32x16_bf16 v[2:17], v[126:129], v[122:125], v[2:17]
	v_lshlrev_b32_e32 v128, 7, v164
	v_or_b32_e32 v126, v128, v168
	v_ashrrev_i32_e32 v127, 31, v126
	v_lshlrev_b64 v[130:131], 2, v[126:127]
	v_lshl_or_b32 v122, v169, 2, v166
	v_or_b32_e32 v124, s3, v168
	v_mov_b32_e32 v125, s5
	s_waitcnt lgkmcnt(0)
	v_mfma_f32_32x32x16_bf16 v[18:33], v[114:117], v[106:109], v[18:33]
	v_bitop3_b32 v106, v169, v167, 10 bitop3:0x36
	v_lshl_add_u32 v106, v106, 4, v165
	ds_read_b128 v[106:109], v106 offset:55296
	v_lshl_add_u64 v[132:133], s[6:7], 0, v[130:131]
	v_lshl_add_u64 v[130:131], s[92:93], 0, v[130:131]
	v_ashrrev_i32_e32 v123, 31, v122
	v_lshlrev_b64 v[122:123], 1, v[122:123]
	v_mfma_f32_32x32x16_bf16 v[2:17], v[114:117], v[110:113], v[2:17]
	s_add_i32 s3, s3, s18
	s_cmpk_gt_i32 s4, 0x7f
	s_waitcnt lgkmcnt(0)
	v_mfma_f32_32x32x16_bf16 v[18:33], v[106:109], v[98:101], v[18:33]
	v_bitop3_b32 v98, v169, v167, 12 bitop3:0x36
	v_lshl_add_u32 v98, v98, 4, v165
	ds_read_b128 v[98:101], v98 offset:55296
	v_mfma_f32_32x32x16_bf16 v[2:17], v[106:109], v[102:105], v[2:17]
	s_waitcnt lgkmcnt(0)
	v_mfma_f32_32x32x16_bf16 v[2:17], v[98:101], v[94:97], v[2:17]
	v_bitop3_b32 v94, v169, v167, 14 bitop3:0x36
	v_lshl_add_u32 v94, v94, 4, v165
	ds_read_b128 v[94:97], v94 offset:55296
	v_ashrrev_i32_e32 v167, 31, v166
	s_waitcnt lgkmcnt(0)
	v_mfma_f32_32x32x16_bf16 v[2:17], v[94:97], v[90:93], v[2:17]
	v_lshlrev_b64 v[90:91], 2, v[166:167]
	v_lshl_add_u64 v[92:93], s[10:11], 0, v[90:91]
	v_lshl_add_u64 v[90:91], s[40:41], 0, v[90:91]
	v_lshl_add_u64 v[92:93], v[92:93], 0, v[154:155]
	v_lshl_add_u64 v[94:95], v[90:91], 0, v[154:155]
	global_load_dwordx4 v[114:117], v[92:93], off
	global_load_dwordx4 v[118:121], v[94:95], off
	global_load_dwordx4 v[106:109], v[92:93], off offset:32
	global_load_dwordx4 v[110:113], v[94:95], off offset:32
	global_load_dwordx4 v[98:101], v[92:93], off offset:64
	global_load_dwordx4 v[102:105], v[94:95], off offset:64
	s_nop 0
	global_load_dwordx4 v[90:93], v[92:93], off offset:96
	s_nop 0
	global_load_dwordx4 v[94:97], v[94:95], off offset:96
	s_nop 0
	global_load_dword v142, v[132:133], off
	global_load_dword v143, v[132:133], off offset:128
	global_load_dword v144, v[132:133], off offset:256
	global_load_dword v145, v[132:133], off offset:384
	global_load_dword v146, v[130:131], off
	global_load_dword v147, v[130:131], off offset:128
	global_load_dword v148, v[130:131], off offset:256
	global_load_dword v149, v[130:131], off offset:384
	v_lshlrev_b64 v[134:135], 11, v[124:125]
	v_lshl_add_u64 v[134:135], s[62:63], 0, v[134:135]
	v_lshl_add_u64 v[134:135], v[134:135], 0, v[122:123]
	v_add_co_u32_e32 v136, vcc, 0x10000, v134
	s_nop 1
	v_addc_co_u32_e32 v137, vcc, 0, v135, vcc
	v_add_co_u32_e32 v138, vcc, 0x20000, v134
	s_nop 1
	v_addc_co_u32_e32 v139, vcc, 0, v135, vcc
	v_add_co_u32_e32 v140, vcc, 0x30000, v134
	s_nop 1
	v_addc_co_u32_e32 v141, vcc, 0, v135, vcc
	v_and_b32_e32 v150, 31, v0
	v_lshlrev_b32_e32 v170, 6, v150
	v_bfe_u32 v151, v0, 5, 1
	v_lshl_add_u32 v170, v151, 3, v170
	v_lshrrev_b32_e32 v168, 6, v0
	v_lshl_add_u32 v170, v168, 13, v170
	v_add_u32_e32 v170, 0xd820, v170
	v_bfe_u32 v150, v0, 1, 2
	v_xor_b32_e32 v151, 0, v150
	v_lshl_add_u32 v152, v151, 4, v170
	v_xor_b32_e32 v151, 1, v150
	v_lshl_add_u32 v153, v151, 4, v170
	v_xor_b32_e32 v151, 2, v150
	v_lshl_add_u32 v164, v151, 4, v170
	v_xor_b32_e32 v151, 3, v150
	v_lshl_add_u32 v165, v151, 4, v170
	v_bfe_u32 v169, v0, 2, 4
	v_lshlrev_b32_e32 v166, 6, v169
	v_and_b32_e32 v151, 3, v0
	v_bfe_u32 v150, v0, 3, 2
	v_xor_b32_e32 v150, v151, v150
	v_lshl_add_u32 v166, v150, 4, v166
	v_lshl_add_u32 v166, v168, 13, v166
	v_add_u32_e32 v166, 0xd820, v166
	v_and_b32_e32 v167, -32, v124
	v_add_u32_e32 v167, v167, v169
	v_lshlrev_b32_e32 v167, 11, v167
	v_lshl_add_u32 v167, v168, 6, v167
	v_lshl_add_u32 v167, v151, 4, v167
	s_waitcnt vmcnt(0)
	s_nop 1
	v_permlane32_swap_b32 v216, v218
	v_permlane32_swap_b32 v217, v219
	v_permlane32_swap_b32 v220, v222
	v_permlane32_swap_b32 v221, v223
	v_permlane32_swap_b32 v224, v226
	v_permlane32_swap_b32 v225, v227
	v_permlane32_swap_b32 v228, v230
	v_permlane32_swap_b32 v229, v231
	v_permlane32_swap_b32 v232, v234
	v_permlane32_swap_b32 v233, v235
	v_permlane32_swap_b32 v236, v238
	v_permlane32_swap_b32 v237, v239
	v_permlane32_swap_b32 v252, v254
	v_permlane32_swap_b32 v253, v255
	v_mul_f32_e32 v150, v118, v142
	v_fmac_f32_e32 v150, v50, v114
	v_add_f32_e32 v50, v146, v150
	v_lshlrev_b32_e32 v151, 16, v216
	v_mul_f32_e32 v50, v50, v151
	v_mul_f32_e32 v150, v119, v142
	v_fmac_f32_e32 v150, v51, v115
	v_add_f32_e32 v51, v146, v150
	v_and_b32_e32 v151, 0xffff0000, v216
	v_mul_f32_e32 v51, v51, v151
	v_mul_f32_e32 v150, v120, v142
	v_fmac_f32_e32 v150, v52, v116
	v_add_f32_e32 v52, v146, v150
	v_lshlrev_b32_e32 v151, 16, v217
	v_mul_f32_e32 v52, v52, v151
	v_mul_f32_e32 v150, v121, v142
	v_fmac_f32_e32 v150, v53, v117
	v_add_f32_e32 v53, v146, v150
	v_and_b32_e32 v151, 0xffff0000, v217
	v_mul_f32_e32 v53, v53, v151
	v_cvt_pk_bf16_f32 v50, v50, v51
	v_cvt_pk_bf16_f32 v51, v52, v53
	ds_write_b64 v152, v[50:51] offset:0
	v_mul_f32_e32 v150, v110, v142
	v_fmac_f32_e32 v150, v54, v106
	v_add_f32_e32 v54, v146, v150
	v_lshlrev_b32_e32 v151, 16, v218
	v_mul_f32_e32 v54, v54, v151
	v_mul_f32_e32 v150, v111, v142
	v_fmac_f32_e32 v150, v55, v107
	v_add_f32_e32 v55, v146, v150
	v_and_b32_e32 v151, 0xffff0000, v218
	v_mul_f32_e32 v55, v55, v151
	v_mul_f32_e32 v150, v112, v142
	v_fmac_f32_e32 v150, v56, v108
	v_add_f32_e32 v56, v146, v150
	v_lshlrev_b32_e32 v151, 16, v219
	v_mul_f32_e32 v56, v56, v151
	v_mul_f32_e32 v150, v113, v142
	v_fmac_f32_e32 v150, v57, v109
	v_add_f32_e32 v57, v146, v150
	v_and_b32_e32 v151, 0xffff0000, v219
	v_mul_f32_e32 v57, v57, v151
	v_cvt_pk_bf16_f32 v54, v54, v55
	v_cvt_pk_bf16_f32 v55, v56, v57
	ds_write_b64 v153, v[54:55] offset:0
	v_mul_f32_e32 v150, v102, v142
	v_fmac_f32_e32 v150, v58, v98
	v_add_f32_e32 v58, v146, v150
	v_lshlrev_b32_e32 v151, 16, v220
	v_mul_f32_e32 v58, v58, v151
	v_mul_f32_e32 v150, v103, v142
	v_fmac_f32_e32 v150, v59, v99
	v_add_f32_e32 v59, v146, v150
	v_and_b32_e32 v151, 0xffff0000, v220
	v_mul_f32_e32 v59, v59, v151
	v_mul_f32_e32 v150, v104, v142
	v_fmac_f32_e32 v150, v60, v100
	v_add_f32_e32 v60, v146, v150
	v_lshlrev_b32_e32 v151, 16, v221
	v_mul_f32_e32 v60, v60, v151
	v_mul_f32_e32 v150, v105, v142
	v_fmac_f32_e32 v150, v61, v101
	v_add_f32_e32 v61, v146, v150
	v_and_b32_e32 v151, 0xffff0000, v221
	v_mul_f32_e32 v61, v61, v151
	v_cvt_pk_bf16_f32 v58, v58, v59
	v_cvt_pk_bf16_f32 v59, v60, v61
	ds_write_b64 v164, v[58:59] offset:0
	v_mul_f32_e32 v150, v94, v142
	v_fmac_f32_e32 v150, v62, v90
	v_add_f32_e32 v62, v146, v150
	v_lshlrev_b32_e32 v151, 16, v222
	v_mul_f32_e32 v62, v62, v151
	v_mul_f32_e32 v150, v95, v142
	v_fmac_f32_e32 v150, v63, v91
	v_add_f32_e32 v63, v146, v150
	v_and_b32_e32 v151, 0xffff0000, v222
	v_mul_f32_e32 v63, v63, v151
	v_mul_f32_e32 v150, v96, v142
	v_fmac_f32_e32 v150, v64, v92
	v_add_f32_e32 v64, v146, v150
	v_lshlrev_b32_e32 v151, 16, v223
	v_mul_f32_e32 v64, v64, v151
	v_mul_f32_e32 v150, v97, v142
	v_fmac_f32_e32 v150, v65, v93
	v_add_f32_e32 v65, v146, v150
	v_and_b32_e32 v151, 0xffff0000, v223
	v_mul_f32_e32 v65, v65, v151
	v_cvt_pk_bf16_f32 v62, v62, v63
	v_cvt_pk_bf16_f32 v63, v64, v65
	ds_write_b64 v165, v[62:63] offset:0
	v_mul_f32_e32 v150, v118, v143
	v_fmac_f32_e32 v150, v34, v114
	v_add_f32_e32 v34, v147, v150
	v_lshlrev_b32_e32 v151, 16, v224
	v_mul_f32_e32 v34, v34, v151
	v_mul_f32_e32 v150, v119, v143
	v_fmac_f32_e32 v150, v35, v115
	v_add_f32_e32 v35, v147, v150
	v_and_b32_e32 v151, 0xffff0000, v224
	v_mul_f32_e32 v35, v35, v151
	v_mul_f32_e32 v150, v120, v143
	v_fmac_f32_e32 v150, v36, v116
	v_add_f32_e32 v36, v147, v150
	v_lshlrev_b32_e32 v151, 16, v225
	v_mul_f32_e32 v36, v36, v151
	v_mul_f32_e32 v150, v121, v143
	v_fmac_f32_e32 v150, v37, v117
	v_add_f32_e32 v37, v147, v150
	v_and_b32_e32 v151, 0xffff0000, v225
	v_mul_f32_e32 v37, v37, v151
	v_cvt_pk_bf16_f32 v34, v34, v35
	v_cvt_pk_bf16_f32 v35, v36, v37
	ds_write_b64 v152, v[34:35] offset:2048
	v_mul_f32_e32 v150, v110, v143
	v_fmac_f32_e32 v150, v38, v106
	v_add_f32_e32 v38, v147, v150
	v_lshlrev_b32_e32 v151, 16, v226
	v_mul_f32_e32 v38, v38, v151
	v_mul_f32_e32 v150, v111, v143
	v_fmac_f32_e32 v150, v39, v107
	v_add_f32_e32 v39, v147, v150
	v_and_b32_e32 v151, 0xffff0000, v226
	v_mul_f32_e32 v39, v39, v151
	v_mul_f32_e32 v150, v112, v143
	v_fmac_f32_e32 v150, v40, v108
	v_add_f32_e32 v40, v147, v150
	v_lshlrev_b32_e32 v151, 16, v227
	v_mul_f32_e32 v40, v40, v151
	v_mul_f32_e32 v150, v113, v143
	v_fmac_f32_e32 v150, v41, v109
	v_add_f32_e32 v41, v147, v150
	v_and_b32_e32 v151, 0xffff0000, v227
	v_mul_f32_e32 v41, v41, v151
	v_cvt_pk_bf16_f32 v38, v38, v39
	v_cvt_pk_bf16_f32 v39, v40, v41
	ds_write_b64 v153, v[38:39] offset:2048
	v_mul_f32_e32 v150, v102, v143
	v_fmac_f32_e32 v150, v42, v98
	v_add_f32_e32 v42, v147, v150
	v_lshlrev_b32_e32 v151, 16, v228
	v_mul_f32_e32 v42, v42, v151
	v_mul_f32_e32 v150, v103, v143
	v_fmac_f32_e32 v150, v43, v99
	v_add_f32_e32 v43, v147, v150
	v_and_b32_e32 v151, 0xffff0000, v228
	v_mul_f32_e32 v43, v43, v151
	v_mul_f32_e32 v150, v104, v143
	v_fmac_f32_e32 v150, v44, v100
	v_add_f32_e32 v44, v147, v150
	v_lshlrev_b32_e32 v151, 16, v229
	v_mul_f32_e32 v44, v44, v151
	v_mul_f32_e32 v150, v105, v143
	v_fmac_f32_e32 v150, v45, v101
	v_add_f32_e32 v45, v147, v150
	v_and_b32_e32 v151, 0xffff0000, v229
	v_mul_f32_e32 v45, v45, v151
	v_cvt_pk_bf16_f32 v42, v42, v43
	v_cvt_pk_bf16_f32 v43, v44, v45
	ds_write_b64 v164, v[42:43] offset:2048
	v_mul_f32_e32 v150, v94, v143
	v_fmac_f32_e32 v150, v46, v90
	v_add_f32_e32 v46, v147, v150
	v_lshlrev_b32_e32 v151, 16, v230
	v_mul_f32_e32 v46, v46, v151
	v_mul_f32_e32 v150, v95, v143
	v_fmac_f32_e32 v150, v47, v91
	v_add_f32_e32 v47, v147, v150
	v_and_b32_e32 v151, 0xffff0000, v230
	v_mul_f32_e32 v47, v47, v151
	v_mul_f32_e32 v150, v96, v143
	v_fmac_f32_e32 v150, v48, v92
	v_add_f32_e32 v48, v147, v150
	v_lshlrev_b32_e32 v151, 16, v231
	v_mul_f32_e32 v48, v48, v151
	v_mul_f32_e32 v150, v97, v143
	v_fmac_f32_e32 v150, v49, v93
	v_add_f32_e32 v49, v147, v150
	v_and_b32_e32 v151, 0xffff0000, v231
	v_mul_f32_e32 v49, v49, v151
	v_cvt_pk_bf16_f32 v46, v46, v47
	v_cvt_pk_bf16_f32 v47, v48, v49
	ds_write_b64 v165, v[46:47] offset:2048
	v_mul_f32_e32 v150, v118, v144
	v_fmac_f32_e32 v150, v18, v114
	v_add_f32_e32 v18, v148, v150
	v_lshlrev_b32_e32 v151, 16, v232
	v_mul_f32_e32 v18, v18, v151
	v_mul_f32_e32 v150, v119, v144
	v_fmac_f32_e32 v150, v19, v115
	v_add_f32_e32 v19, v148, v150
	v_and_b32_e32 v151, 0xffff0000, v232
	v_mul_f32_e32 v19, v19, v151
	v_mul_f32_e32 v150, v120, v144
	v_fmac_f32_e32 v150, v20, v116
	v_add_f32_e32 v20, v148, v150
	v_lshlrev_b32_e32 v151, 16, v233
	v_mul_f32_e32 v20, v20, v151
	v_mul_f32_e32 v150, v121, v144
	v_fmac_f32_e32 v150, v21, v117
	v_add_f32_e32 v21, v148, v150
	v_and_b32_e32 v151, 0xffff0000, v233
	v_mul_f32_e32 v21, v21, v151
	v_cvt_pk_bf16_f32 v18, v18, v19
	v_cvt_pk_bf16_f32 v19, v20, v21
	ds_write_b64 v152, v[18:19] offset:4096
	v_mul_f32_e32 v150, v110, v144
	v_fmac_f32_e32 v150, v22, v106
	v_add_f32_e32 v22, v148, v150
	v_lshlrev_b32_e32 v151, 16, v234
	v_mul_f32_e32 v22, v22, v151
	v_mul_f32_e32 v150, v111, v144
	v_fmac_f32_e32 v150, v23, v107
	v_add_f32_e32 v23, v148, v150
	v_and_b32_e32 v151, 0xffff0000, v234
	v_mul_f32_e32 v23, v23, v151
	v_mul_f32_e32 v150, v112, v144
	v_fmac_f32_e32 v150, v24, v108
	v_add_f32_e32 v24, v148, v150
	v_lshlrev_b32_e32 v151, 16, v235
	v_mul_f32_e32 v24, v24, v151
	v_mul_f32_e32 v150, v113, v144
	v_fmac_f32_e32 v150, v25, v109
	v_add_f32_e32 v25, v148, v150
	v_and_b32_e32 v151, 0xffff0000, v235
	v_mul_f32_e32 v25, v25, v151
	v_cvt_pk_bf16_f32 v22, v22, v23
	v_cvt_pk_bf16_f32 v23, v24, v25
	ds_write_b64 v153, v[22:23] offset:4096
	v_mul_f32_e32 v150, v102, v144
	v_fmac_f32_e32 v150, v26, v98
	v_add_f32_e32 v26, v148, v150
	v_lshlrev_b32_e32 v151, 16, v236
	v_mul_f32_e32 v26, v26, v151
	v_mul_f32_e32 v150, v103, v144
	v_fmac_f32_e32 v150, v27, v99
	v_add_f32_e32 v27, v148, v150
	v_and_b32_e32 v151, 0xffff0000, v236
	v_mul_f32_e32 v27, v27, v151
	v_mul_f32_e32 v150, v104, v144
	v_fmac_f32_e32 v150, v28, v100
	v_add_f32_e32 v28, v148, v150
	v_lshlrev_b32_e32 v151, 16, v237
	v_mul_f32_e32 v28, v28, v151
	v_mul_f32_e32 v150, v105, v144
	v_fmac_f32_e32 v150, v29, v101
	v_add_f32_e32 v29, v148, v150
	v_and_b32_e32 v151, 0xffff0000, v237
	v_mul_f32_e32 v29, v29, v151
	v_cvt_pk_bf16_f32 v26, v26, v27
	v_cvt_pk_bf16_f32 v27, v28, v29
	ds_write_b64 v164, v[26:27] offset:4096
	v_mul_f32_e32 v150, v94, v144
	v_fmac_f32_e32 v150, v30, v90
	v_add_f32_e32 v30, v148, v150
	v_lshlrev_b32_e32 v151, 16, v238
	v_mul_f32_e32 v30, v30, v151
	v_mul_f32_e32 v150, v95, v144
	v_fmac_f32_e32 v150, v31, v91
	v_add_f32_e32 v31, v148, v150
	v_and_b32_e32 v151, 0xffff0000, v238
	v_mul_f32_e32 v31, v31, v151
	v_mul_f32_e32 v150, v96, v144
	v_fmac_f32_e32 v150, v32, v92
	v_add_f32_e32 v32, v148, v150
	v_lshlrev_b32_e32 v151, 16, v239
	v_mul_f32_e32 v32, v32, v151
	v_mul_f32_e32 v150, v97, v144
	v_fmac_f32_e32 v150, v33, v93
	v_add_f32_e32 v33, v148, v150
	v_and_b32_e32 v151, 0xffff0000, v239
	v_mul_f32_e32 v33, v33, v151
	v_cvt_pk_bf16_f32 v30, v30, v31
	v_cvt_pk_bf16_f32 v31, v32, v33
	ds_write_b64 v165, v[30:31] offset:4096
	v_mul_f32_e32 v150, v118, v145
	v_fmac_f32_e32 v150, v2, v114
	v_add_f32_e32 v2, v149, v150
	v_lshlrev_b32_e32 v151, 16, v252
	v_mul_f32_e32 v2, v2, v151
	v_mul_f32_e32 v150, v119, v145
	v_fmac_f32_e32 v150, v3, v115
	v_add_f32_e32 v3, v149, v150
	v_and_b32_e32 v151, 0xffff0000, v252
	v_mul_f32_e32 v3, v3, v151
	v_mul_f32_e32 v150, v120, v145
	v_fmac_f32_e32 v150, v4, v116
	v_add_f32_e32 v4, v149, v150
	v_lshlrev_b32_e32 v151, 16, v253
	v_mul_f32_e32 v4, v4, v151
	v_mul_f32_e32 v150, v121, v145
	v_fmac_f32_e32 v150, v5, v117
	v_add_f32_e32 v5, v149, v150
	v_and_b32_e32 v151, 0xffff0000, v253
	v_mul_f32_e32 v5, v5, v151
	v_cvt_pk_bf16_f32 v2, v2, v3
	v_cvt_pk_bf16_f32 v3, v4, v5
	ds_write_b64 v152, v[2:3] offset:6144
	v_mul_f32_e32 v150, v110, v145
	v_fmac_f32_e32 v150, v6, v106
	v_add_f32_e32 v6, v149, v150
	v_lshlrev_b32_e32 v151, 16, v254
	v_mul_f32_e32 v6, v6, v151
	v_mul_f32_e32 v150, v111, v145
	v_fmac_f32_e32 v150, v7, v107
	v_add_f32_e32 v7, v149, v150
	v_and_b32_e32 v151, 0xffff0000, v254
	v_mul_f32_e32 v7, v7, v151
	v_mul_f32_e32 v150, v112, v145
	v_fmac_f32_e32 v150, v8, v108
	v_add_f32_e32 v8, v149, v150
	v_lshlrev_b32_e32 v151, 16, v255
	v_mul_f32_e32 v8, v8, v151
	v_mul_f32_e32 v150, v113, v145
	v_fmac_f32_e32 v150, v9, v109
	v_add_f32_e32 v9, v149, v150
	v_and_b32_e32 v151, 0xffff0000, v255
	v_mul_f32_e32 v9, v9, v151
	v_cvt_pk_bf16_f32 v6, v6, v7
	v_cvt_pk_bf16_f32 v7, v8, v9
	ds_write_b64 v153, v[6:7] offset:6144
	v_mul_f32_e32 v150, v102, v145
	v_fmac_f32_e32 v150, v10, v98
	v_add_f32_e32 v10, v149, v150
	v_lshlrev_b32_e32 v151, 16, v240
	v_mul_f32_e32 v10, v10, v151
	v_mul_f32_e32 v150, v103, v145
	v_fmac_f32_e32 v150, v11, v99
	v_add_f32_e32 v11, v149, v150
	v_and_b32_e32 v151, 0xffff0000, v240
	v_mul_f32_e32 v11, v11, v151
	v_mul_f32_e32 v150, v104, v145
	v_fmac_f32_e32 v150, v12, v100
	v_add_f32_e32 v12, v149, v150
	v_lshlrev_b32_e32 v151, 16, v241
	v_mul_f32_e32 v12, v12, v151
	v_mul_f32_e32 v150, v105, v145
	v_fmac_f32_e32 v150, v13, v101
	v_add_f32_e32 v13, v149, v150
	v_and_b32_e32 v151, 0xffff0000, v241
	v_mul_f32_e32 v13, v13, v151
	v_cvt_pk_bf16_f32 v10, v10, v11
	v_cvt_pk_bf16_f32 v11, v12, v13
	ds_write_b64 v164, v[10:11] offset:6144
	v_mul_f32_e32 v150, v94, v145
	v_fmac_f32_e32 v150, v14, v90
	v_add_f32_e32 v14, v149, v150
	v_lshlrev_b32_e32 v151, 16, v246
	v_mul_f32_e32 v14, v14, v151
	v_mul_f32_e32 v150, v95, v145
	v_fmac_f32_e32 v150, v15, v91
	v_add_f32_e32 v15, v149, v150
	v_and_b32_e32 v151, 0xffff0000, v246
	v_mul_f32_e32 v15, v15, v151
	v_mul_f32_e32 v150, v96, v145
	v_fmac_f32_e32 v150, v16, v92
	v_add_f32_e32 v16, v149, v150
	v_lshlrev_b32_e32 v151, 16, v247
	v_mul_f32_e32 v16, v16, v151
	v_mul_f32_e32 v150, v97, v145
	v_fmac_f32_e32 v150, v17, v93
	v_add_f32_e32 v17, v149, v150
	v_and_b32_e32 v151, 0xffff0000, v247
	v_mul_f32_e32 v17, v17, v151
	v_cvt_pk_bf16_f32 v14, v14, v15
	v_cvt_pk_bf16_f32 v15, v16, v17
	ds_write_b64 v165, v[14:15] offset:6144
	s_waitcnt lgkmcnt(0)
	ds_read_b128 v[2:5], v166 offset:0
	ds_read_b128 v[6:9], v166 offset:1024
	ds_read_b128 v[10:13], v166 offset:2048
	ds_read_b128 v[14:17], v166 offset:3072
	ds_read_b128 v[18:21], v166 offset:4096
	ds_read_b128 v[22:25], v166 offset:5120
	ds_read_b128 v[26:29], v166 offset:6144
	ds_read_b128 v[30:33], v166 offset:7168
	s_waitcnt lgkmcnt(7)
	global_store_dwordx4 v167, v[2:5], s[62:63] offset:1536
	v_add_u32_e32 v151, 0x8000, v167
	s_waitcnt lgkmcnt(6)
	global_store_dwordx4 v151, v[6:9], s[62:63] offset:1536
	v_add_u32_e32 v150, 0x10000, v167
	s_waitcnt lgkmcnt(5)
	global_store_dwordx4 v150, v[10:13], s[62:63] offset:1536
	v_add_u32_e32 v151, 0x18000, v167
	s_waitcnt lgkmcnt(4)
	global_store_dwordx4 v151, v[14:17], s[62:63] offset:1536
	v_add_u32_e32 v150, 0x20000, v167
	s_waitcnt lgkmcnt(3)
	global_store_dwordx4 v150, v[18:21], s[62:63] offset:1536
	v_add_u32_e32 v151, 0x28000, v167
	s_waitcnt lgkmcnt(2)
	global_store_dwordx4 v151, v[22:25], s[62:63] offset:1536
	v_add_u32_e32 v150, 0x30000, v167
	s_waitcnt lgkmcnt(1)
	global_store_dwordx4 v150, v[26:29], s[62:63] offset:1536
	v_add_u32_e32 v151, 0x38000, v167
	s_waitcnt lgkmcnt(0)
	global_store_dwordx4 v151, v[30:33], s[62:63] offset:1536
	s_barrier
	s_cbranch_scc0 .LBB0_779

.LBB0_849:
	v_mov_b32_e32 v43, v0
	s_ashr_i32 s5, s3, 31
	v_ashrrev_i32_e32 v44, 7, v43
	s_waitcnt vmcnt(7)
	v_add_u32_e32 v130, s2, v44
	v_ashrrev_i32_e32 v131, 31, v130
	v_and_b32_e32 v134, 31, v43
	s_waitcnt vmcnt(0)
	v_lshlrev_b64 v[2:3], 15, v[130:131]
	v_bfe_u32 v135, v43, 5, 1
	v_lshl_add_u64 v[2:3], s[56:57], 0, v[2:3]
	v_and_b32_e32 v18, 63, v43
	v_lshlrev_b32_e32 v18, 4, v18
	v_lshlrev_b32_e32 v154, 4, v135
	v_add_u32_e32 v18, 0x1000, v18
	v_add_co_u32_e32 v18, vcc, v2, v18
	s_nop 1
	v_addc_co_u32_e32 v19, vcc, 0, v3, vcc
	v_add_co_u32_e32 v20, vcc, s14, v18
	v_ashrrev_i32_e32 v45, 2, v43
	s_nop 0
	v_addc_co_u32_e32 v21, vcc, 0, v19, vcc
	v_add_co_u32_e32 v22, vcc, s17, v18
	global_load_dwordx4 v[2:5], v[18:19], off offset:-4096
	global_load_dwordx4 v[6:9], v[20:21], off offset:-4096
	v_addc_co_u32_e32 v23, vcc, 0, v19, vcc
	v_add_co_u32_e32 v24, vcc, s30, v18
	global_load_dwordx4 v[10:13], v[22:23], off offset:-4096
	s_nop 0
	v_addc_co_u32_e32 v25, vcc, 0, v19, vcc
	global_load_dwordx4 v[14:17], v[24:25], off offset:-4096
	global_load_dwordx4 v[114:117], v[18:19], off offset:-3072
	global_load_dwordx4 v[118:121], v[20:21], off offset:-3072
	global_load_dwordx4 v[122:125], v[22:23], off offset:-3072
	global_load_dwordx4 v[126:129], v[24:25], off offset:-3072
	global_load_dwordx4 v[102:105], v[20:21], off offset:-2048
	global_load_dwordx4 v[106:109], v[22:23], off offset:-2048
	global_load_dwordx4 v[110:113], v[24:25], off offset:-2048
	global_load_dwordx4 v[90:93], v[20:21], off offset:-1024
	global_load_dwordx4 v[94:97], v[22:23], off offset:-1024
	global_load_dwordx4 v[98:101], v[24:25], off offset:-1024
	global_load_dwordx4 v[82:85], v[22:23], off
	global_load_dwordx4 v[86:89], v[24:25], off
	global_load_dwordx4 v[74:77], v[22:23], off offset:1024
	global_load_dwordx4 v[78:81], v[24:25], off offset:1024
	global_load_dwordx4 v[70:73], v[24:25], off offset:2048
	global_load_dwordx4 v[66:69], v[24:25], off offset:3072
	v_add_u32_e32 v18, s3, v45
	v_ashrrev_i32_e32 v19, 31, v18
	v_lshlrev_b32_e32 v20, 6, v43
	v_lshlrev_b64 v[18:19], 12, v[18:19]
	v_and_b32_e32 v46, 0xc0, v20
	v_lshl_add_u64 v[18:19], s[60:61], 0, v[18:19]
	v_lshlrev_b32_e32 v20, 1, v46
	v_mov_b32_e32 v21, v155
	v_lshl_add_u64 v[34:35], v[18:19], 0, v[20:21]
	global_load_dwordx4 v[18:21], v[34:35], off offset:3632
	global_load_dwordx4 v[22:25], v[34:35], off offset:3616
	global_load_dwordx4 v[26:29], v[34:35], off offset:3600
	global_load_dwordx4 v[30:33], v[34:35], off offset:3584
	global_load_dwordx4 v[36:39], v[34:35], off offset:3680
	global_load_dwordx4 v[176:179], v[34:35], off offset:3664
	global_load_dwordx4 v[48:51], v[34:35], off offset:3648
	global_load_dwordx4 v[182:185], v[34:35], off offset:3696
	v_lshrrev_b32_e32 v42, 5, v43
	s_add_i32 s4, s4, s46
	s_waitcnt vmcnt(7)
	v_lshlrev_b32_e32 v144, 16, v18
	s_waitcnt vmcnt(6)
	v_lshlrev_b32_e32 v150, 16, v22
	s_waitcnt vmcnt(5)
	v_lshlrev_b32_e32 v168, 16, v26
	s_waitcnt vmcnt(4)
	v_lshlrev_b32_e32 v174, 16, v30
	v_and_b32_e32 v173, 0xffff0000, v30
	v_add_f32_e32 v30, 0, v174
	v_lshlrev_b32_e32 v172, 16, v31
	v_add_f32_e32 v30, v30, v173
	v_and_b32_e32 v171, 0xffff0000, v31
	v_mul_f32_e32 v31, v173, v173
	v_add_f32_e32 v30, v30, v172
	v_lshlrev_b32_e32 v170, 16, v32
	v_fmac_f32_e32 v31, v174, v174
	v_add_f32_e32 v30, v30, v171
	v_and_b32_e32 v169, 0xffff0000, v32
	v_fmac_f32_e32 v31, v172, v172
	v_add_f32_e32 v30, v30, v170
	v_lshlrev_b32_e32 v167, 16, v33
	v_fmac_f32_e32 v31, v171, v171
	v_add_f32_e32 v30, v30, v169
	v_and_b32_e32 v165, 0xffff0000, v33
	v_fmac_f32_e32 v31, v170, v170
	v_add_f32_e32 v30, v30, v167
	v_fmac_f32_e32 v31, v169, v169
	v_add_f32_e32 v30, v30, v165
	v_fmac_f32_e32 v31, v167, v167
	v_and_b32_e32 v166, 0xffff0000, v26
	v_add_f32_e32 v26, v30, v168
	v_fmac_f32_e32 v31, v165, v165
	v_lshlrev_b32_e32 v164, 16, v27
	v_add_f32_e32 v26, v26, v166
	v_and_b32_e32 v153, 0xffff0000, v27
	v_fmac_f32_e32 v31, v168, v168
	v_add_f32_e32 v26, v26, v164
	v_lshlrev_b32_e32 v152, 16, v28
	v_fmac_f32_e32 v31, v166, v166
	v_add_f32_e32 v26, v26, v153
	v_and_b32_e32 v151, 0xffff0000, v28
	v_fmac_f32_e32 v31, v164, v164
	v_add_f32_e32 v26, v26, v152
	v_lshlrev_b32_e32 v148, 16, v29
	v_fmac_f32_e32 v31, v153, v153
	v_add_f32_e32 v26, v26, v151
	v_and_b32_e32 v146, 0xffff0000, v29
	v_fmac_f32_e32 v31, v152, v152
	v_add_f32_e32 v26, v26, v148
	v_fmac_f32_e32 v31, v151, v151
	v_add_f32_e32 v26, v26, v146
	v_fmac_f32_e32 v31, v148, v148
	v_and_b32_e32 v149, 0xffff0000, v22
	v_add_f32_e32 v22, v26, v150
	v_fmac_f32_e32 v31, v146, v146
	v_lshlrev_b32_e32 v147, 16, v23
	v_add_f32_e32 v22, v22, v149
	v_and_b32_e32 v145, 0xffff0000, v23
	v_fmac_f32_e32 v31, v150, v150
	v_add_f32_e32 v22, v22, v147
	v_lshlrev_b32_e32 v143, 16, v24
	v_fmac_f32_e32 v31, v149, v149
	v_add_f32_e32 v22, v22, v145
	v_and_b32_e32 v141, 0xffff0000, v24
	v_fmac_f32_e32 v31, v147, v147
	v_add_f32_e32 v22, v22, v143
	v_lshlrev_b32_e32 v139, 16, v25
	v_fmac_f32_e32 v31, v145, v145
	v_add_f32_e32 v22, v22, v141
	v_and_b32_e32 v137, 0xffff0000, v25
	v_fmac_f32_e32 v31, v143, v143
	v_add_f32_e32 v22, v22, v139
	v_fmac_f32_e32 v31, v141, v141
	v_add_f32_e32 v22, v22, v137
	v_fmac_f32_e32 v31, v139, v139
	v_and_b32_e32 v142, 0xffff0000, v18
	v_add_f32_e32 v18, v22, v144
	v_fmac_f32_e32 v31, v137, v137
	v_lshlrev_b32_e32 v140, 16, v19
	v_add_f32_e32 v18, v18, v142
	v_and_b32_e32 v138, 0xffff0000, v19
	v_fmac_f32_e32 v31, v144, v144
	v_add_f32_e32 v18, v18, v140
	v_lshlrev_b32_e32 v133, 16, v20
	v_fmac_f32_e32 v31, v142, v142
	v_add_f32_e32 v18, v18, v138
	v_and_b32_e32 v131, 0xffff0000, v20
	v_fmac_f32_e32 v31, v140, v140
	v_add_f32_e32 v18, v18, v133
	v_lshlrev_b32_e32 v64, 16, v21
	v_fmac_f32_e32 v31, v138, v138
	v_add_f32_e32 v18, v18, v131
	v_and_b32_e32 v62, 0xffff0000, v21
	v_fmac_f32_e32 v31, v133, v133
	v_add_f32_e32 v18, v18, v64
	v_fmac_f32_e32 v31, v131, v131
	v_add_f32_e32 v18, v18, v62
	s_waitcnt vmcnt(1)
	v_lshlrev_b32_e32 v136, 16, v48
	v_fmac_f32_e32 v31, v64, v64
	v_and_b32_e32 v132, 0xffff0000, v48
	v_add_f32_e32 v18, v18, v136
	v_fmac_f32_e32 v31, v62, v62
	v_lshlrev_b32_e32 v65, 16, v49
	v_add_f32_e32 v18, v18, v132
	v_and_b32_e32 v63, 0xffff0000, v49
	v_fmac_f32_e32 v31, v136, v136
	v_add_f32_e32 v18, v18, v65
	v_lshlrev_b32_e32 v60, 16, v50
	v_fmac_f32_e32 v31, v132, v132
	v_add_f32_e32 v18, v18, v63
	v_and_b32_e32 v59, 0xffff0000, v50
	v_fmac_f32_e32 v31, v65, v65
	v_add_f32_e32 v18, v18, v60
	v_lshlrev_b32_e32 v57, 16, v51
	v_fmac_f32_e32 v31, v63, v63
	v_add_f32_e32 v18, v18, v59
	v_and_b32_e32 v55, 0xffff0000, v51
	v_fmac_f32_e32 v31, v60, v60
	v_add_f32_e32 v18, v18, v57
	v_fmac_f32_e32 v31, v59, v59
	v_add_f32_e32 v18, v18, v55
	v_lshlrev_b32_e32 v61, 16, v176
	v_fmac_f32_e32 v31, v57, v57
	v_and_b32_e32 v58, 0xffff0000, v176
	v_add_f32_e32 v18, v18, v61
	v_fmac_f32_e32 v31, v55, v55
	v_lshlrev_b32_e32 v56, 16, v177
	v_add_f32_e32 v18, v18, v58
	v_and_b32_e32 v54, 0xffff0000, v177
	v_fmac_f32_e32 v31, v61, v61
	v_add_f32_e32 v18, v18, v56
	v_lshlrev_b32_e32 v53, 16, v178
	v_fmac_f32_e32 v31, v58, v58
	v_add_f32_e32 v18, v18, v54
	v_and_b32_e32 v51, 0xffff0000, v178
	v_fmac_f32_e32 v31, v56, v56
	v_add_f32_e32 v18, v18, v53
	v_lshlrev_b32_e32 v49, 16, v179
	v_fmac_f32_e32 v31, v54, v54
	v_add_f32_e32 v18, v18, v51
	v_and_b32_e32 v47, 0xffff0000, v179
	v_fmac_f32_e32 v31, v53, v53
	v_add_f32_e32 v18, v18, v49
	v_fmac_f32_e32 v31, v51, v51
	v_add_f32_e32 v18, v18, v47
	v_lshlrev_b32_e32 v52, 16, v36
	v_fmac_f32_e32 v31, v49, v49
	v_and_b32_e32 v50, 0xffff0000, v36
	v_add_f32_e32 v18, v18, v52
	v_fmac_f32_e32 v31, v47, v47
	v_lshlrev_b32_e32 v48, 16, v37
	v_add_f32_e32 v18, v18, v50
	v_fmac_f32_e32 v31, v52, v52
	v_add_f32_e32 v18, v18, v48
	v_and_b32_e32 v37, 0xffff0000, v37
	v_fmac_f32_e32 v31, v50, v50
	v_lshlrev_b32_e32 v34, 16, v38
	v_mov_b32_e32 v35, v37
	v_add_f32_e32 v20, v18, v37
	v_fmac_f32_e32 v31, v48, v48
	v_and_b32_e32 v24, 0xffff0000, v38
	v_pk_mul_f32 v[18:19], v[34:35], v[34:35]
	v_add_f32_e32 v20, v20, v34
	v_lshlrev_b32_e32 v25, 16, v39
	v_add_f32_e32 v19, v19, v31
	v_add_f32_e32 v20, v20, v24
	v_add_f32_e32 v21, v18, v19
	v_pk_mul_f32 v[18:19], v[24:25], v[24:25]
	v_add_f32_e32 v20, v20, v25
	v_and_b32_e32 v33, 0xffff0000, v39
	v_add_f32_e32 v18, v18, v21
	s_waitcnt vmcnt(0)
	v_lshlrev_b32_e32 v28, 16, v182
	v_mov_b32_e32 v29, v33
	v_add_f32_e32 v20, v20, v33
	v_add_f32_e32 v21, v19, v18
	v_and_b32_e32 v22, 0xffff0000, v182
	v_pk_mul_f32 v[18:19], v[28:29], v[28:29]
	v_add_f32_e32 v20, v20, v28
	v_lshlrev_b32_e32 v23, 16, v183
	v_add_f32_e32 v19, v19, v21
	v_add_f32_e32 v20, v20, v22
	v_add_f32_e32 v21, v18, v19
	v_pk_mul_f32 v[18:19], v[22:23], v[22:23]
	v_add_f32_e32 v29, v20, v23
	v_and_b32_e32 v31, 0xffff0000, v183
	v_add_f32_e32 v18, v18, v21
	v_lshlrev_b32_e32 v26, 16, v184
	v_mov_b32_e32 v27, v31
	v_add_f32_e32 v29, v29, v31
	v_and_b32_e32 v36, s0, v38
	v_add_f32_e32 v18, v19, v18
	v_and_b32_e32 v20, 0xffff0000, v184
	v_pk_mul_f32 v[38:39], v[26:27], v[26:27]
	v_add_f32_e32 v27, v29, v26
	v_lshlrev_b32_e32 v21, 16, v185
	v_add_f32_e32 v18, v39, v18
	v_add_f32_e32 v27, v27, v20
	v_and_b32_e32 v29, 64, v181
	v_add_f32_e32 v18, v38, v18
	v_pk_mul_f32 v[40:41], v[20:21], v[20:21]
	v_add_f32_e32 v39, v27, v21
	v_xor_b32_e32 v27, 1, v181
	v_add_u32_e32 v29, 64, v29
	v_and_b32_e32 v19, 0xffff0000, v185
	v_add_f32_e32 v18, v40, v18
	v_cmp_lt_i32_e32 vcc, v27, v29
	v_add_f32_e32 v18, v41, v18
	v_mul_f32_e32 v38, v19, v19
	v_cndmask_b32_e32 v27, v181, v27, vcc
	v_lshlrev_b32_e32 v27, 2, v27
	v_pk_add_f32 v[38:39], v[38:39], v[18:19]
	s_nop 1
	v_mov_b32_dpp v41, v39 quad_perm:[1,0,3,2] row_mask:0xf bank_mask:0xf
	v_mov_b32_dpp v40, v38 quad_perm:[1,0,3,2] row_mask:0xf bank_mask:0xf
	v_xor_b32_e32 v35, 2, v181
	v_cmp_lt_i32_e32 vcc, v35, v29
	v_and_b32_e32 v30, s0, v182
	v_mov_b32_e32 v32, v36
	v_cndmask_b32_e32 v29, v181, v35, vcc
	v_lshlrev_b32_e32 v29, 2, v29
	s_waitcnt lgkmcnt(0)
	v_pk_add_f32 v[38:39], v[38:39], v[40:41]
	s_nop 1
	v_mov_b32_dpp v41, v39 quad_perm:[2,3,0,1] row_mask:0xf bank_mask:0xf
	v_mov_b32_dpp v40, v38 quad_perm:[2,3,0,1] row_mask:0xf bank_mask:0xf
	s_waitcnt lgkmcnt(0)
	v_pk_add_f32 v[40:41], v[38:39], v[40:41]
	s_nop 0
	v_pk_mul_f32 v[38:39], v[40:41], s[22:23] op_sel_hi:[1,0]
	v_pk_fma_f32 v[36:37], v[40:41], s[22:23], v[36:37] op_sel_hi:[1,0,1] neg_lo:[1,0,0] neg_hi:[1,0,0]
	v_fma_f32 v18, -v39, v39, v38
	v_max_f32_e32 v18, 0, v18
	v_add_f32_e32 v18, 0x358637bd, v18
	v_cmp_gt_f32_e32 vcc, s33, v18
	v_mul_f32_e32 v27, 0x4b800000, v18
	v_sub_f32_e32 v29, v174, v39
	v_cndmask_b32_e32 v18, v18, v27, vcc
	v_rsq_f32_e32 v18, v18
	v_sub_f32_e32 v19, v19, v39
	v_mul_f32_e32 v27, 0x45800000, v18
	v_cndmask_b32_e32 v18, v18, v27, vcc
	v_mul_f32_e32 v29, v29, v18
	v_lshlrev_b32_e32 v27, 1, v45
	v_bfe_u32 v35, v29, 16, 1
	v_ashrrev_i32_e32 v45, 1, v43
	v_and_b32_e32 v27, 14, v27
	v_add3_u32 v29, v29, v35, s15
	v_lshl_add_u32 v35, v46, 8, 32
	v_and_b32_e32 v46, -16, v45
	v_add3_u32 v174, v35, v46, v27
	ds_write_b16_d16_hi v174, v29 offset:55296
	v_mul_f32_e64 v215, -v39, v18
	v_fma_f32 v29, v173, v18, v215
	v_cvt_pk_bf16_f32 v29, v29, v29
	v_bitop3_b32 v173, v45, 16, -16 bitop3:0x6c
	v_add3_u32 v175, v35, v173, v27
	ds_write_b16 v175, v29 offset:55552
	v_fma_f32 v29, v172, v18, v215
	v_cvt_pk_bf16_f32 v29, v29, v29
	v_bitop3_b32 v172, v45, 32, -16 bitop3:0x6c
	v_add3_u32 v176, v35, v172, v27
	ds_write_b16 v176, v29 offset:55808
	v_fma_f32 v29, v171, v18, v215
	v_cvt_pk_bf16_f32 v29, v29, v29
	v_bitop3_b32 v171, v45, 48, -16 bitop3:0x6c
	v_add3_u32 v177, v35, v171, v27
	ds_write_b16 v177, v29 offset:56064
	v_fma_f32 v29, v170, v18, v215
	v_cvt_pk_bf16_f32 v29, v29, v29
	v_bitop3_b32 v170, v45, 64, -16 bitop3:0x6c
	v_add3_u32 v178, v35, v170, v27
	ds_write_b16 v178, v29 offset:56320
	v_fma_f32 v29, v169, v18, v215
	v_cvt_pk_bf16_f32 v29, v29, v29
	v_bitop3_b32 v169, v45, s34, -16 bitop3:0x6c
	v_add3_u32 v179, v35, v169, v27
	ds_write_b16 v179, v29 offset:56576
	v_fma_f32 v29, v167, v18, v215
	v_cvt_pk_bf16_f32 v29, v29, v29
	v_bitop3_b32 v167, v45, s31, -16 bitop3:0x6c
	v_add3_u32 v182, v35, v167, v27
	ds_write_b16 v182, v29 offset:56832
	v_fma_f32 v29, v165, v18, v215
	v_cvt_pk_bf16_f32 v29, v29, v29
	v_bitop3_b32 v165, v45, s13, -16 bitop3:0x6c
	v_add3_u32 v183, v35, v165, v27
	ds_write_b16 v183, v29 offset:57088
	v_fma_f32 v29, v168, v18, v215
	v_cvt_pk_bf16_f32 v29, v29, v29
	v_bitop3_b32 v168, v45, s12, -16 bitop3:0x6c
	v_add3_u32 v184, v35, v168, v27
	ds_write_b16 v184, v29 offset:57344
	v_fma_f32 v29, v166, v18, v215
	v_cvt_pk_bf16_f32 v29, v29, v29
	v_bitop3_b32 v166, v45, s35, -16 bitop3:0x6c
	v_add3_u32 v185, v35, v166, v27
	ds_write_b16 v185, v29 offset:57600
	v_fma_f32 v29, v164, v18, v215
	v_cvt_pk_bf16_f32 v29, v29, v29
	v_bitop3_b32 v164, v45, s38, -16 bitop3:0x6c
	v_add3_u32 v186, v35, v164, v27
	ds_write_b16 v186, v29 offset:57856
	v_fma_f32 v29, v153, v18, v215
	v_cvt_pk_bf16_f32 v29, v29, v29
	v_bitop3_b32 v153, v45, s39, -16 bitop3:0x6c
	v_add3_u32 v187, v35, v153, v27
	ds_write_b16 v187, v29 offset:58112
	v_fma_f32 v29, v152, v18, v215
	v_cvt_pk_bf16_f32 v29, v29, v29
	v_bitop3_b32 v152, v45, s16, -16 bitop3:0x6c
	v_add3_u32 v188, v35, v152, v27
	ds_write_b16 v188, v29 offset:58368
	v_fma_f32 v29, v151, v18, v215
	v_cvt_pk_bf16_f32 v29, v29, v29
	v_bitop3_b32 v151, v45, s40, -16 bitop3:0x6c
	v_add3_u32 v189, v35, v151, v27
	ds_write_b16 v189, v29 offset:58624
	v_fma_f32 v29, v148, v18, v215
	v_cvt_pk_bf16_f32 v29, v29, v29
	v_bitop3_b32 v148, v45, s41, -16 bitop3:0x6c
	v_add3_u32 v190, v35, v148, v27
	ds_write_b16 v190, v29 offset:58880
	v_sub_f32_e32 v29, v146, v39
	v_mul_f32_e32 v29, v29, v18
	v_bfe_u32 v146, v29, 16, 1
	v_bitop3_b32 v45, v45, s42, -16 bitop3:0x6c
	v_add_u32_e32 v38, 0xd800, v35
	v_add3_u32 v29, v29, v146, s15
	v_add3_u32 v35, v35, v45, v27
	ds_write_b16_d16_hi v35, v29 offset:59136
	v_fma_f32 v29, v150, v18, v215
	v_cvt_pk_bf16_f32 v29, v29, v29
	ds_write_b16 v174, v29 offset:59392
	v_fma_f32 v29, v149, v18, v215
	v_cvt_pk_bf16_f32 v29, v29, v29
	ds_write_b16 v175, v29 offset:59648
	v_fma_f32 v29, v147, v18, v215
	v_cvt_pk_bf16_f32 v29, v29, v29
	ds_write_b16 v176, v29 offset:59904
	v_fma_f32 v29, v145, v18, v215
	v_cvt_pk_bf16_f32 v29, v29, v29
	ds_write_b16 v177, v29 offset:60160
	v_fma_f32 v29, v143, v18, v215
	v_cvt_pk_bf16_f32 v29, v29, v29
	ds_write_b16 v178, v29 offset:60416
	v_fma_f32 v29, v141, v18, v215
	v_cvt_pk_bf16_f32 v29, v29, v29
	ds_write_b16 v179, v29 offset:60672
	v_fma_f32 v29, v139, v18, v215
	v_cvt_pk_bf16_f32 v29, v29, v29
	ds_write_b16 v182, v29 offset:60928
	v_fma_f32 v29, v137, v18, v215
	v_cvt_pk_bf16_f32 v29, v29, v29
	ds_write_b16 v183, v29 offset:61184
	v_fma_f32 v29, v144, v18, v215
	v_cvt_pk_bf16_f32 v29, v29, v29
	ds_write_b16 v184, v29 offset:61440
	v_fma_f32 v29, v142, v18, v215
	v_cvt_pk_bf16_f32 v29, v29, v29
	ds_write_b16 v185, v29 offset:61696
	v_fma_f32 v29, v140, v18, v215
	v_cvt_pk_bf16_f32 v29, v29, v29
	ds_write_b16 v186, v29 offset:61952
	v_fma_f32 v29, v138, v18, v215
	v_cvt_pk_bf16_f32 v29, v29, v29
	ds_write_b16 v187, v29 offset:62208
	v_fma_f32 v29, v133, v18, v215
	v_cvt_pk_bf16_f32 v29, v29, v29
	ds_write_b16 v188, v29 offset:62464
	v_fma_f32 v29, v131, v18, v215
	v_cvt_pk_bf16_f32 v29, v29, v29
	ds_write_b16 v189, v29 offset:62720
	v_fma_f32 v29, v64, v18, v215
	v_cvt_pk_bf16_f32 v29, v29, v29
	ds_write_b16 v190, v29 offset:62976
	v_fma_f32 v29, v62, v18, v215
	v_cvt_pk_bf16_f32 v29, v29, v29
	ds_write_b16 v35, v29 offset:63232
	v_fma_f32 v29, v136, v18, v215
	v_cvt_pk_bf16_f32 v29, v29, v29
	ds_write_b16 v174, v29 offset:63488
	v_fma_f32 v29, v132, v18, v215
	v_cvt_pk_bf16_f32 v29, v29, v29
	ds_write_b16 v175, v29 offset:63744
	v_fma_f32 v29, v65, v18, v215
	v_cvt_pk_bf16_f32 v29, v29, v29
	ds_write_b16 v176, v29 offset:64000
	v_fma_f32 v29, v63, v18, v215
	v_cvt_pk_bf16_f32 v29, v29, v29
	ds_write_b16 v177, v29 offset:64256
	v_fma_f32 v29, v60, v18, v215
	v_cvt_pk_bf16_f32 v29, v29, v29
	ds_write_b16 v178, v29 offset:64512
	v_fma_f32 v29, v59, v18, v215
	v_cvt_pk_bf16_f32 v29, v29, v29
	ds_write_b16 v179, v29 offset:64768
	v_fma_f32 v29, v57, v18, v215
	v_cvt_pk_bf16_f32 v29, v29, v29
	ds_write_b16 v182, v29 offset:65024
	v_fma_f32 v29, v55, v18, v215
	v_cvt_pk_bf16_f32 v29, v29, v29
	ds_write_b16 v183, v29 offset:65280
	v_fma_f32 v29, v61, v18, v215
	v_cvt_pk_bf16_f32 v29, v29, v29
	v_add3_u32 v35, v38, v168, v27
	ds_write_b16 v35, v29 offset:10240
	v_fma_f32 v29, v58, v18, v215
	v_cvt_pk_bf16_f32 v29, v29, v29
	v_add3_u32 v55, v38, v166, v27
	ds_write_b16 v55, v29 offset:10496
	v_fma_f32 v29, v56, v18, v215
	v_cvt_pk_bf16_f32 v29, v29, v29
	v_add3_u32 v56, v38, v164, v27
	ds_write_b16 v56, v29 offset:10752
	v_fma_f32 v29, v54, v18, v215
	v_cvt_pk_bf16_f32 v29, v29, v29
	v_add3_u32 v54, v38, v153, v27
	ds_write_b16 v54, v29 offset:11008
	v_fma_f32 v29, v53, v18, v215
	v_cvt_pk_bf16_f32 v29, v29, v29
	v_add3_u32 v53, v38, v152, v27
	ds_write_b16 v53, v29 offset:11264
	v_fma_f32 v29, v51, v18, v215
	v_cvt_pk_bf16_f32 v29, v29, v29
	v_add3_u32 v51, v38, v151, v27
	ds_write_b16 v51, v29 offset:11520
	v_fma_f32 v29, v49, v18, v215
	v_cvt_pk_bf16_f32 v29, v29, v29
	v_add3_u32 v49, v38, v148, v27
	ds_write_b16 v49, v29 offset:11776
	v_fma_f32 v29, v47, v18, v215
	v_cvt_pk_bf16_f32 v29, v29, v29
	v_add3_u32 v45, v38, v45, v27
	ds_write_b16 v45, v29 offset:12032
	v_fma_f32 v29, v52, v18, v215
	v_cvt_pk_bf16_f32 v29, v29, v29
	v_add3_u32 v46, v38, v46, v27
	ds_write_b16 v46, v29 offset:12288
	v_fma_f32 v29, v50, v18, v215
	v_cvt_pk_bf16_f32 v29, v29, v29
	v_add3_u32 v46, v38, v173, v27
	ds_write_b16 v46, v29 offset:12544
	v_fma_f32 v29, v48, v18, v215
	v_cvt_pk_bf16_f32 v29, v29, v29
	v_add3_u32 v46, v38, v172, v27
	ds_write_b16 v46, v29 offset:12800
	v_mul_f32_e32 v29, v37, v18
	v_bfe_u32 v36, v29, 16, 1
	v_add3_u32 v29, v29, v36, s15
	v_add3_u32 v36, v38, v171, v27
	ds_write_b16_d16_hi v36, v29 offset:13056
	v_fma_f32 v29, v34, v18, v215
	v_cvt_pk_bf16_f32 v29, v29, v29
	v_add3_u32 v34, v38, v170, v27
	ds_write_b16 v34, v29 offset:13312
	v_sub_f32_e32 v29, v24, v39
	v_pk_fma_f32 v[24:25], v[40:41], s[22:23], v[24:25] op_sel_hi:[1,0,1] neg_lo:[1,0,0] neg_hi:[1,0,0]
	v_mul_f32_e32 v29, v29, v18
	v_mul_f32_e32 v24, v25, v18
	v_bfe_u32 v34, v29, 16, 1
	v_bfe_u32 v25, v24, 16, 1
	v_add3_u32 v29, v29, v34, s15
	v_add3_u32 v34, v38, v169, v27
	v_add3_u32 v24, v24, v25, s15
	v_add3_u32 v25, v38, v167, v27
	ds_write_b16_d16_hi v34, v29 offset:13568
	ds_write_b16_d16_hi v25, v24 offset:13824
	v_pk_fma_f32 v[24:25], v[40:41], s[22:23], v[32:33] op_sel_hi:[1,0,1] neg_lo:[1,0,0] neg_hi:[1,0,0]
	v_and_b32_e32 v133, 15, v43
	v_mul_f32_e32 v24, v25, v18
	v_bfe_u32 v25, v24, 16, 1
	v_add3_u32 v24, v24, v25, s15
	v_add3_u32 v25, v38, v165, v27
	ds_write_b16_d16_hi v25, v24 offset:14080
	v_fma_f32 v24, v28, v18, v215
	v_cvt_pk_bf16_f32 v24, v24, v24
	ds_write_b16 v35, v24 offset:14336
	v_sub_f32_e32 v24, v22, v39
	v_pk_fma_f32 v[22:23], v[40:41], s[22:23], v[22:23] op_sel_hi:[1,0,1] neg_lo:[1,0,0] neg_hi:[1,0,0]
	v_mul_f32_e32 v24, v24, v18
	v_mul_f32_e32 v22, v23, v18
	v_bfe_u32 v25, v24, 16, 1
	v_bfe_u32 v23, v22, 16, 1
	v_add3_u32 v24, v24, v25, s15
	v_add3_u32 v22, v22, v23, s15
	ds_write_b16_d16_hi v55, v24 offset:14592
	ds_write_b16_d16_hi v56, v22 offset:14848
	v_pk_fma_f32 v[22:23], v[40:41], s[22:23], v[30:31] op_sel_hi:[1,0,1] neg_lo:[1,0,0] neg_hi:[1,0,0]
	s_nop 0
	v_mul_f32_e32 v22, v23, v18
	v_bfe_u32 v23, v22, 16, 1
	v_add3_u32 v22, v22, v23, s15
	ds_write_b16_d16_hi v54, v22 offset:15104
	v_fma_f32 v22, v26, v18, v215
	v_cvt_pk_bf16_f32 v22, v22, v22
	ds_write_b16 v53, v22 offset:15360
	v_sub_f32_e32 v22, v20, v39
	v_pk_fma_f32 v[20:21], v[40:41], s[22:23], v[20:21] op_sel_hi:[1,0,1] neg_lo:[1,0,0] neg_hi:[1,0,0]
	v_mul_f32_e32 v22, v22, v18
	v_mul_f32_e32 v20, v21, v18
	v_mul_f32_e32 v18, v19, v18
	v_bfe_u32 v23, v22, 16, 1
	v_bfe_u32 v21, v20, 16, 1
	v_bfe_u32 v19, v18, 16, 1
	v_add3_u32 v22, v22, v23, s15
	v_add3_u32 v20, v20, v21, s15
	v_add3_u32 v18, v18, v19, s15
	ds_write_b16_d16_hi v51, v22 offset:15616
	ds_write_b16_d16_hi v49, v20 offset:15872
	ds_write_b16_d16_hi v45, v18 offset:16128
	v_lshrrev_b32_e32 v18, 1, v43
	v_and_b32_e32 v18, 32, v18
	v_lshl_or_b32 v132, v44, 6, v18
	v_or_b32_e32 v18, v132, v134
	v_lshl_add_u32 v131, v18, 8, 32
	v_bitop3_b32 v18, v42, v133, 1 bitop3:0x6c
	v_lshl_add_u32 v18, v18, 4, v131
	v_and_b32_e32 v215, 31, v0
	v_add_u32_e32 v215, s3, v215
	v_lshlrev_b32_e32 v215, 12, v215
	v_and_b32_e32 v245, 0x1c0, v0
	v_add_u32_e32 v215, v215, v245
	v_bfe_u32 v245, v0, 5, 1
	v_lshl_add_u32 v245, v245, 3, v215
	v_bfe_u32 v215, v0, 5, 1
	v_lshl_add_u32 v215, v215, 3, v245
	global_load_dwordx4 v[216:219], v215, s[60:61] offset:3072
	global_load_dwordx4 v[220:223], v215, s[60:61] offset:3104
	s_add_u32 s98, s60, 0x20000
	s_addc_u32 s99, s61, 0
	global_load_dwordx4 v[224:227], v215, s[98:99] offset:3072
	global_load_dwordx4 v[228:231], v215, s[98:99] offset:3104
	s_add_u32 s100, s60, 0x40000
	s_addc_u32 s101, s61, 0
	global_load_dwordx4 v[232:235], v215, s[100:101] offset:3072
	global_load_dwordx4 v[236:239], v215, s[100:101] offset:3104
	s_add_u32 s98, s60, 0x60000
	s_addc_u32 s99, s61, 0
	global_load_dwordx4 v[252:255], v215, s[98:99] offset:3072
	global_load_dwordx2 v[240:241], v245, s[98:99] offset:3104
	global_load_dwordx2 v[246:247], v245, s[98:99] offset:3120
	s_waitcnt lgkmcnt(0)
	s_barrier
	ds_read_b128 v[136:139], v18 offset:55296
	s_waitcnt lgkmcnt(0)
	v_mfma_f32_32x32x16_bf16 v[50:65], v[136:139], v[2:5], 0
	v_mfma_f32_32x32x16_bf16 v[34:49], v[136:139], v[6:9], 0
	v_mfma_f32_32x32x16_bf16 v[18:33], v[136:139], v[10:13], 0
	v_mfma_f32_32x32x16_bf16 v[2:17], v[136:139], v[14:17], 0
	v_bitop3_b32 v136, v135, v133, 2 bitop3:0x36
	v_lshl_add_u32 v136, v136, 4, v131
	ds_read_b128 v[136:139], v136 offset:55296
	s_waitcnt lgkmcnt(0)
	v_mfma_f32_32x32x16_bf16 v[50:65], v[136:139], v[114:117], v[50:65]
	v_bitop3_b32 v114, v135, v133, 4 bitop3:0x36
	v_lshl_add_u32 v114, v114, 4, v131
	ds_read_b128 v[114:117], v114 offset:55296
	v_mfma_f32_32x32x16_bf16 v[34:49], v[136:139], v[118:121], v[34:49]
	v_mfma_f32_32x32x16_bf16 v[18:33], v[136:139], v[122:125], v[18:33]
	s_waitcnt lgkmcnt(0)
	v_mfma_f32_32x32x16_bf16 v[34:49], v[114:117], v[102:105], v[34:49]
	v_bitop3_b32 v102, v135, v133, 6 bitop3:0x36
	v_lshl_add_u32 v102, v102, 4, v131
	ds_read_b128 v[102:105], v102 offset:55296
	v_mfma_f32_32x32x16_bf16 v[2:17], v[136:139], v[126:129], v[2:17]
	v_mfma_f32_32x32x16_bf16 v[18:33], v[114:117], v[106:109], v[18:33]
	s_waitcnt lgkmcnt(0)
	v_mfma_f32_32x32x16_bf16 v[34:49], v[102:105], v[90:93], v[34:49]
	v_bitop3_b32 v90, v135, v133, 8 bitop3:0x36
	v_lshl_add_u32 v90, v90, 4, v131
	ds_read_b128 v[90:93], v90 offset:55296
	v_mfma_f32_32x32x16_bf16 v[2:17], v[114:117], v[110:113], v[2:17]
	v_mfma_f32_32x32x16_bf16 v[18:33], v[102:105], v[94:97], v[18:33]
	v_mfma_f32_32x32x16_bf16 v[2:17], v[102:105], v[98:101], v[2:17]
	v_lshlrev_b32_e32 v104, 7, v130
	v_or_b32_e32 v102, v104, v134
	v_ashrrev_i32_e32 v103, 31, v102
	v_lshlrev_b64 v[106:107], 2, v[102:103]
	v_lshl_or_b32 v98, v135, 2, v132
	v_or_b32_e32 v100, s3, v134
	v_mov_b32_e32 v101, s5
	s_waitcnt lgkmcnt(0)
	v_mfma_f32_32x32x16_bf16 v[18:33], v[90:93], v[82:85], v[18:33]
	v_bitop3_b32 v82, v135, v133, 10 bitop3:0x36
	v_lshl_add_u32 v82, v82, 4, v131
	ds_read_b128 v[82:85], v82 offset:55296
	v_lshl_add_u64 v[108:109], s[6:7], 0, v[106:107]
	v_lshl_add_u64 v[106:107], s[92:93], 0, v[106:107]
	v_ashrrev_i32_e32 v99, 31, v98
	v_lshlrev_b64 v[98:99], 1, v[98:99]
	v_mfma_f32_32x32x16_bf16 v[2:17], v[90:93], v[86:89], v[2:17]
	s_add_i32 s3, s3, s18
	s_cmpk_gt_i32 s4, 0x7f
	s_waitcnt lgkmcnt(0)
	v_mfma_f32_32x32x16_bf16 v[18:33], v[82:85], v[74:77], v[18:33]
	v_bitop3_b32 v74, v135, v133, 12 bitop3:0x36
	v_lshl_add_u32 v74, v74, 4, v131
	ds_read_b128 v[74:77], v74 offset:55296
	v_mfma_f32_32x32x16_bf16 v[2:17], v[82:85], v[78:81], v[2:17]
	s_waitcnt lgkmcnt(0)
	v_mfma_f32_32x32x16_bf16 v[2:17], v[74:77], v[70:73], v[2:17]
	v_bitop3_b32 v70, v135, v133, 14 bitop3:0x36
	v_lshl_add_u32 v70, v70, 4, v131
	ds_read_b128 v[70:73], v70 offset:55296
	v_ashrrev_i32_e32 v133, 31, v132
	s_waitcnt lgkmcnt(0)
	v_mfma_f32_32x32x16_bf16 v[2:17], v[70:73], v[66:69], v[2:17]
	v_lshlrev_b64 v[66:67], 2, v[132:133]
	v_lshl_add_u64 v[68:69], s[10:11], 0, v[66:67]
	v_lshl_add_u64 v[66:67], s[36:37], 0, v[66:67]
	v_lshl_add_u64 v[68:69], v[68:69], 0, v[154:155]
	v_lshl_add_u64 v[70:71], v[66:67], 0, v[154:155]
	global_load_dwordx4 v[90:93], v[68:69], off
	global_load_dwordx4 v[94:97], v[70:71], off
	global_load_dwordx4 v[82:85], v[68:69], off offset:32
	global_load_dwordx4 v[86:89], v[70:71], off offset:32
	global_load_dwordx4 v[74:77], v[68:69], off offset:64
	global_load_dwordx4 v[78:81], v[70:71], off offset:64
	s_nop 0
	global_load_dwordx4 v[66:69], v[68:69], off offset:96
	s_nop 0
	global_load_dwordx4 v[70:73], v[70:71], off offset:96
	s_nop 0
	global_load_dword v118, v[108:109], off
	global_load_dword v119, v[108:109], off offset:128
	global_load_dword v120, v[108:109], off offset:256
	global_load_dword v121, v[108:109], off offset:384
	global_load_dword v122, v[106:107], off
	global_load_dword v123, v[106:107], off offset:128
	global_load_dword v124, v[106:107], off offset:256
	global_load_dword v125, v[106:107], off offset:384
	v_lshlrev_b64 v[110:111], 11, v[100:101]
	v_lshl_add_u64 v[110:111], s[62:63], 0, v[110:111]
	v_lshl_add_u64 v[110:111], v[110:111], 0, v[98:99]
	v_add_co_u32_e32 v112, vcc, 0x10000, v110
	s_nop 1
	v_addc_co_u32_e32 v113, vcc, 0, v111, vcc
	v_add_co_u32_e32 v114, vcc, 0x20000, v110
	s_nop 1
	v_addc_co_u32_e32 v115, vcc, 0, v111, vcc
	v_add_co_u32_e32 v116, vcc, 0x30000, v110
	s_nop 1
	v_addc_co_u32_e32 v117, vcc, 0, v111, vcc
	v_and_b32_e32 v126, 31, v0
	v_lshlrev_b32_e32 v136, 6, v126
	v_bfe_u32 v127, v0, 5, 1
	v_lshl_add_u32 v136, v127, 3, v136
	v_lshrrev_b32_e32 v134, 6, v0
	v_lshl_add_u32 v136, v134, 13, v136
	v_add_u32_e32 v136, 0xd820, v136
	v_bfe_u32 v126, v0, 1, 2
	v_xor_b32_e32 v127, 0, v126
	v_lshl_add_u32 v128, v127, 4, v136
	v_xor_b32_e32 v127, 1, v126
	v_lshl_add_u32 v129, v127, 4, v136
	v_xor_b32_e32 v127, 2, v126
	v_lshl_add_u32 v130, v127, 4, v136
	v_xor_b32_e32 v127, 3, v126
	v_lshl_add_u32 v131, v127, 4, v136
	v_bfe_u32 v135, v0, 2, 4
	v_lshlrev_b32_e32 v132, 6, v135
	v_and_b32_e32 v127, 3, v0
	v_bfe_u32 v126, v0, 3, 2
	v_xor_b32_e32 v126, v127, v126
	v_lshl_add_u32 v132, v126, 4, v132
	v_lshl_add_u32 v132, v134, 13, v132
	v_add_u32_e32 v132, 0xd820, v132
	v_and_b32_e32 v133, -32, v100
	v_add_u32_e32 v133, v133, v135
	v_lshlrev_b32_e32 v133, 11, v133
	v_lshl_add_u32 v133, v134, 6, v133
	v_lshl_add_u32 v133, v127, 4, v133
	s_waitcnt vmcnt(0)
	s_nop 1
	v_permlane32_swap_b32 v216, v218
	v_permlane32_swap_b32 v217, v219
	v_permlane32_swap_b32 v220, v222
	v_permlane32_swap_b32 v221, v223
	v_permlane32_swap_b32 v224, v226
	v_permlane32_swap_b32 v225, v227
	v_permlane32_swap_b32 v228, v230
	v_permlane32_swap_b32 v229, v231
	v_permlane32_swap_b32 v232, v234
	v_permlane32_swap_b32 v233, v235
	v_permlane32_swap_b32 v236, v238
	v_permlane32_swap_b32 v237, v239
	v_permlane32_swap_b32 v252, v254
	v_permlane32_swap_b32 v253, v255
	v_mul_f32_e32 v126, v94, v118
	v_fmac_f32_e32 v126, v50, v90
	v_add_f32_e32 v50, v122, v126
	v_lshlrev_b32_e32 v127, 16, v216
	v_mul_f32_e32 v50, v50, v127
	v_mul_f32_e32 v126, v95, v118
	v_fmac_f32_e32 v126, v51, v91
	v_add_f32_e32 v51, v122, v126
	v_and_b32_e32 v127, 0xffff0000, v216
	v_mul_f32_e32 v51, v51, v127
	v_mul_f32_e32 v126, v96, v118
	v_fmac_f32_e32 v126, v52, v92
	v_add_f32_e32 v52, v122, v126
	v_lshlrev_b32_e32 v127, 16, v217
	v_mul_f32_e32 v52, v52, v127
	v_mul_f32_e32 v126, v97, v118
	v_fmac_f32_e32 v126, v53, v93
	v_add_f32_e32 v53, v122, v126
	v_and_b32_e32 v127, 0xffff0000, v217
	v_mul_f32_e32 v53, v53, v127
	v_cvt_pk_bf16_f32 v50, v50, v51
	v_cvt_pk_bf16_f32 v51, v52, v53
	ds_write_b64 v128, v[50:51] offset:0
	v_mul_f32_e32 v126, v86, v118
	v_fmac_f32_e32 v126, v54, v82
	v_add_f32_e32 v54, v122, v126
	v_lshlrev_b32_e32 v127, 16, v218
	v_mul_f32_e32 v54, v54, v127
	v_mul_f32_e32 v126, v87, v118
	v_fmac_f32_e32 v126, v55, v83
	v_add_f32_e32 v55, v122, v126
	v_and_b32_e32 v127, 0xffff0000, v218
	v_mul_f32_e32 v55, v55, v127
	v_mul_f32_e32 v126, v88, v118
	v_fmac_f32_e32 v126, v56, v84
	v_add_f32_e32 v56, v122, v126
	v_lshlrev_b32_e32 v127, 16, v219
	v_mul_f32_e32 v56, v56, v127
	v_mul_f32_e32 v126, v89, v118
	v_fmac_f32_e32 v126, v57, v85
	v_add_f32_e32 v57, v122, v126
	v_and_b32_e32 v127, 0xffff0000, v219
	v_mul_f32_e32 v57, v57, v127
	v_cvt_pk_bf16_f32 v54, v54, v55
	v_cvt_pk_bf16_f32 v55, v56, v57
	ds_write_b64 v129, v[54:55] offset:0
	v_mul_f32_e32 v126, v78, v118
	v_fmac_f32_e32 v126, v58, v74
	v_add_f32_e32 v58, v122, v126
	v_lshlrev_b32_e32 v127, 16, v220
	v_mul_f32_e32 v58, v58, v127
	v_mul_f32_e32 v126, v79, v118
	v_fmac_f32_e32 v126, v59, v75
	v_add_f32_e32 v59, v122, v126
	v_and_b32_e32 v127, 0xffff0000, v220
	v_mul_f32_e32 v59, v59, v127
	v_mul_f32_e32 v126, v80, v118
	v_fmac_f32_e32 v126, v60, v76
	v_add_f32_e32 v60, v122, v126
	v_lshlrev_b32_e32 v127, 16, v221
	v_mul_f32_e32 v60, v60, v127
	v_mul_f32_e32 v126, v81, v118
	v_fmac_f32_e32 v126, v61, v77
	v_add_f32_e32 v61, v122, v126
	v_and_b32_e32 v127, 0xffff0000, v221
	v_mul_f32_e32 v61, v61, v127
	v_cvt_pk_bf16_f32 v58, v58, v59
	v_cvt_pk_bf16_f32 v59, v60, v61
	ds_write_b64 v130, v[58:59] offset:0
	v_mul_f32_e32 v126, v70, v118
	v_fmac_f32_e32 v126, v62, v66
	v_add_f32_e32 v62, v122, v126
	v_lshlrev_b32_e32 v127, 16, v222
	v_mul_f32_e32 v62, v62, v127
	v_mul_f32_e32 v126, v71, v118
	v_fmac_f32_e32 v126, v63, v67
	v_add_f32_e32 v63, v122, v126
	v_and_b32_e32 v127, 0xffff0000, v222
	v_mul_f32_e32 v63, v63, v127
	v_mul_f32_e32 v126, v72, v118
	v_fmac_f32_e32 v126, v64, v68
	v_add_f32_e32 v64, v122, v126
	v_lshlrev_b32_e32 v127, 16, v223
	v_mul_f32_e32 v64, v64, v127
	v_mul_f32_e32 v126, v73, v118
	v_fmac_f32_e32 v126, v65, v69
	v_add_f32_e32 v65, v122, v126
	v_and_b32_e32 v127, 0xffff0000, v223
	v_mul_f32_e32 v65, v65, v127
	v_cvt_pk_bf16_f32 v62, v62, v63
	v_cvt_pk_bf16_f32 v63, v64, v65
	ds_write_b64 v131, v[62:63] offset:0
	v_mul_f32_e32 v126, v94, v119
	v_fmac_f32_e32 v126, v34, v90
	v_add_f32_e32 v34, v123, v126
	v_lshlrev_b32_e32 v127, 16, v224
	v_mul_f32_e32 v34, v34, v127
	v_mul_f32_e32 v126, v95, v119
	v_fmac_f32_e32 v126, v35, v91
	v_add_f32_e32 v35, v123, v126
	v_and_b32_e32 v127, 0xffff0000, v224
	v_mul_f32_e32 v35, v35, v127
	v_mul_f32_e32 v126, v96, v119
	v_fmac_f32_e32 v126, v36, v92
	v_add_f32_e32 v36, v123, v126
	v_lshlrev_b32_e32 v127, 16, v225
	v_mul_f32_e32 v36, v36, v127
	v_mul_f32_e32 v126, v97, v119
	v_fmac_f32_e32 v126, v37, v93
	v_add_f32_e32 v37, v123, v126
	v_and_b32_e32 v127, 0xffff0000, v225
	v_mul_f32_e32 v37, v37, v127
	v_cvt_pk_bf16_f32 v34, v34, v35
	v_cvt_pk_bf16_f32 v35, v36, v37
	ds_write_b64 v128, v[34:35] offset:2048
	v_mul_f32_e32 v126, v86, v119
	v_fmac_f32_e32 v126, v38, v82
	v_add_f32_e32 v38, v123, v126
	v_lshlrev_b32_e32 v127, 16, v226
	v_mul_f32_e32 v38, v38, v127
	v_mul_f32_e32 v126, v87, v119
	v_fmac_f32_e32 v126, v39, v83
	v_add_f32_e32 v39, v123, v126
	v_and_b32_e32 v127, 0xffff0000, v226
	v_mul_f32_e32 v39, v39, v127
	v_mul_f32_e32 v126, v88, v119
	v_fmac_f32_e32 v126, v40, v84
	v_add_f32_e32 v40, v123, v126
	v_lshlrev_b32_e32 v127, 16, v227
	v_mul_f32_e32 v40, v40, v127
	v_mul_f32_e32 v126, v89, v119
	v_fmac_f32_e32 v126, v41, v85
	v_add_f32_e32 v41, v123, v126
	v_and_b32_e32 v127, 0xffff0000, v227
	v_mul_f32_e32 v41, v41, v127
	v_cvt_pk_bf16_f32 v38, v38, v39
	v_cvt_pk_bf16_f32 v39, v40, v41
	ds_write_b64 v129, v[38:39] offset:2048
	v_mul_f32_e32 v126, v78, v119
	v_fmac_f32_e32 v126, v42, v74
	v_add_f32_e32 v42, v123, v126
	v_lshlrev_b32_e32 v127, 16, v228
	v_mul_f32_e32 v42, v42, v127
	v_mul_f32_e32 v126, v79, v119
	v_fmac_f32_e32 v126, v43, v75
	v_add_f32_e32 v43, v123, v126
	v_and_b32_e32 v127, 0xffff0000, v228
	v_mul_f32_e32 v43, v43, v127
	v_mul_f32_e32 v126, v80, v119
	v_fmac_f32_e32 v126, v44, v76
	v_add_f32_e32 v44, v123, v126
	v_lshlrev_b32_e32 v127, 16, v229
	v_mul_f32_e32 v44, v44, v127
	v_mul_f32_e32 v126, v81, v119
	v_fmac_f32_e32 v126, v45, v77
	v_add_f32_e32 v45, v123, v126
	v_and_b32_e32 v127, 0xffff0000, v229
	v_mul_f32_e32 v45, v45, v127
	v_cvt_pk_bf16_f32 v42, v42, v43
	v_cvt_pk_bf16_f32 v43, v44, v45
	ds_write_b64 v130, v[42:43] offset:2048
	v_mul_f32_e32 v126, v70, v119
	v_fmac_f32_e32 v126, v46, v66
	v_add_f32_e32 v46, v123, v126
	v_lshlrev_b32_e32 v127, 16, v230
	v_mul_f32_e32 v46, v46, v127
	v_mul_f32_e32 v126, v71, v119
	v_fmac_f32_e32 v126, v47, v67
	v_add_f32_e32 v47, v123, v126
	v_and_b32_e32 v127, 0xffff0000, v230
	v_mul_f32_e32 v47, v47, v127
	v_mul_f32_e32 v126, v72, v119
	v_fmac_f32_e32 v126, v48, v68
	v_add_f32_e32 v48, v123, v126
	v_lshlrev_b32_e32 v127, 16, v231
	v_mul_f32_e32 v48, v48, v127
	v_mul_f32_e32 v126, v73, v119
	v_fmac_f32_e32 v126, v49, v69
	v_add_f32_e32 v49, v123, v126
	v_and_b32_e32 v127, 0xffff0000, v231
	v_mul_f32_e32 v49, v49, v127
	v_cvt_pk_bf16_f32 v46, v46, v47
	v_cvt_pk_bf16_f32 v47, v48, v49
	ds_write_b64 v131, v[46:47] offset:2048
	v_mul_f32_e32 v126, v94, v120
	v_fmac_f32_e32 v126, v18, v90
	v_add_f32_e32 v18, v124, v126
	v_lshlrev_b32_e32 v127, 16, v232
	v_mul_f32_e32 v18, v18, v127
	v_mul_f32_e32 v126, v95, v120
	v_fmac_f32_e32 v126, v19, v91
	v_add_f32_e32 v19, v124, v126
	v_and_b32_e32 v127, 0xffff0000, v232
	v_mul_f32_e32 v19, v19, v127
	v_mul_f32_e32 v126, v96, v120
	v_fmac_f32_e32 v126, v20, v92
	v_add_f32_e32 v20, v124, v126
	v_lshlrev_b32_e32 v127, 16, v233
	v_mul_f32_e32 v20, v20, v127
	v_mul_f32_e32 v126, v97, v120
	v_fmac_f32_e32 v126, v21, v93
	v_add_f32_e32 v21, v124, v126
	v_and_b32_e32 v127, 0xffff0000, v233
	v_mul_f32_e32 v21, v21, v127
	v_cvt_pk_bf16_f32 v18, v18, v19
	v_cvt_pk_bf16_f32 v19, v20, v21
	ds_write_b64 v128, v[18:19] offset:4096
	v_mul_f32_e32 v126, v86, v120
	v_fmac_f32_e32 v126, v22, v82
	v_add_f32_e32 v22, v124, v126
	v_lshlrev_b32_e32 v127, 16, v234
	v_mul_f32_e32 v22, v22, v127
	v_mul_f32_e32 v126, v87, v120
	v_fmac_f32_e32 v126, v23, v83
	v_add_f32_e32 v23, v124, v126
	v_and_b32_e32 v127, 0xffff0000, v234
	v_mul_f32_e32 v23, v23, v127
	v_mul_f32_e32 v126, v88, v120
	v_fmac_f32_e32 v126, v24, v84
	v_add_f32_e32 v24, v124, v126
	v_lshlrev_b32_e32 v127, 16, v235
	v_mul_f32_e32 v24, v24, v127
	v_mul_f32_e32 v126, v89, v120
	v_fmac_f32_e32 v126, v25, v85
	v_add_f32_e32 v25, v124, v126
	v_and_b32_e32 v127, 0xffff0000, v235
	v_mul_f32_e32 v25, v25, v127
	v_cvt_pk_bf16_f32 v22, v22, v23
	v_cvt_pk_bf16_f32 v23, v24, v25
	ds_write_b64 v129, v[22:23] offset:4096
	v_mul_f32_e32 v126, v78, v120
	v_fmac_f32_e32 v126, v26, v74
	v_add_f32_e32 v26, v124, v126
	v_lshlrev_b32_e32 v127, 16, v236
	v_mul_f32_e32 v26, v26, v127
	v_mul_f32_e32 v126, v79, v120
	v_fmac_f32_e32 v126, v27, v75
	v_add_f32_e32 v27, v124, v126
	v_and_b32_e32 v127, 0xffff0000, v236
	v_mul_f32_e32 v27, v27, v127
	v_mul_f32_e32 v126, v80, v120
	v_fmac_f32_e32 v126, v28, v76
	v_add_f32_e32 v28, v124, v126
	v_lshlrev_b32_e32 v127, 16, v237
	v_mul_f32_e32 v28, v28, v127
	v_mul_f32_e32 v126, v81, v120
	v_fmac_f32_e32 v126, v29, v77
	v_add_f32_e32 v29, v124, v126
	v_and_b32_e32 v127, 0xffff0000, v237
	v_mul_f32_e32 v29, v29, v127
	v_cvt_pk_bf16_f32 v26, v26, v27
	v_cvt_pk_bf16_f32 v27, v28, v29
	ds_write_b64 v130, v[26:27] offset:4096
	v_mul_f32_e32 v126, v70, v120
	v_fmac_f32_e32 v126, v30, v66
	v_add_f32_e32 v30, v124, v126
	v_lshlrev_b32_e32 v127, 16, v238
	v_mul_f32_e32 v30, v30, v127
	v_mul_f32_e32 v126, v71, v120
	v_fmac_f32_e32 v126, v31, v67
	v_add_f32_e32 v31, v124, v126
	v_and_b32_e32 v127, 0xffff0000, v238
	v_mul_f32_e32 v31, v31, v127
	v_mul_f32_e32 v126, v72, v120
	v_fmac_f32_e32 v126, v32, v68
	v_add_f32_e32 v32, v124, v126
	v_lshlrev_b32_e32 v127, 16, v239
	v_mul_f32_e32 v32, v32, v127
	v_mul_f32_e32 v126, v73, v120
	v_fmac_f32_e32 v126, v33, v69
	v_add_f32_e32 v33, v124, v126
	v_and_b32_e32 v127, 0xffff0000, v239
	v_mul_f32_e32 v33, v33, v127
	v_cvt_pk_bf16_f32 v30, v30, v31
	v_cvt_pk_bf16_f32 v31, v32, v33
	ds_write_b64 v131, v[30:31] offset:4096
	v_mul_f32_e32 v126, v94, v121
	v_fmac_f32_e32 v126, v2, v90
	v_add_f32_e32 v2, v125, v126
	v_lshlrev_b32_e32 v127, 16, v252
	v_mul_f32_e32 v2, v2, v127
	v_mul_f32_e32 v126, v95, v121
	v_fmac_f32_e32 v126, v3, v91
	v_add_f32_e32 v3, v125, v126
	v_and_b32_e32 v127, 0xffff0000, v252
	v_mul_f32_e32 v3, v3, v127
	v_mul_f32_e32 v126, v96, v121
	v_fmac_f32_e32 v126, v4, v92
	v_add_f32_e32 v4, v125, v126
	v_lshlrev_b32_e32 v127, 16, v253
	v_mul_f32_e32 v4, v4, v127
	v_mul_f32_e32 v126, v97, v121
	v_fmac_f32_e32 v126, v5, v93
	v_add_f32_e32 v5, v125, v126
	v_and_b32_e32 v127, 0xffff0000, v253
	v_mul_f32_e32 v5, v5, v127
	v_cvt_pk_bf16_f32 v2, v2, v3
	v_cvt_pk_bf16_f32 v3, v4, v5
	ds_write_b64 v128, v[2:3] offset:6144
	v_mul_f32_e32 v126, v86, v121
	v_fmac_f32_e32 v126, v6, v82
	v_add_f32_e32 v6, v125, v126
	v_lshlrev_b32_e32 v127, 16, v254
	v_mul_f32_e32 v6, v6, v127
	v_mul_f32_e32 v126, v87, v121
	v_fmac_f32_e32 v126, v7, v83
	v_add_f32_e32 v7, v125, v126
	v_and_b32_e32 v127, 0xffff0000, v254
	v_mul_f32_e32 v7, v7, v127
	v_mul_f32_e32 v126, v88, v121
	v_fmac_f32_e32 v126, v8, v84
	v_add_f32_e32 v8, v125, v126
	v_lshlrev_b32_e32 v127, 16, v255
	v_mul_f32_e32 v8, v8, v127
	v_mul_f32_e32 v126, v89, v121
	v_fmac_f32_e32 v126, v9, v85
	v_add_f32_e32 v9, v125, v126
	v_and_b32_e32 v127, 0xffff0000, v255
	v_mul_f32_e32 v9, v9, v127
	v_cvt_pk_bf16_f32 v6, v6, v7
	v_cvt_pk_bf16_f32 v7, v8, v9
	ds_write_b64 v129, v[6:7] offset:6144
	v_mul_f32_e32 v126, v78, v121
	v_fmac_f32_e32 v126, v10, v74
	v_add_f32_e32 v10, v125, v126
	v_lshlrev_b32_e32 v127, 16, v240
	v_mul_f32_e32 v10, v10, v127
	v_mul_f32_e32 v126, v79, v121
	v_fmac_f32_e32 v126, v11, v75
	v_add_f32_e32 v11, v125, v126
	v_and_b32_e32 v127, 0xffff0000, v240
	v_mul_f32_e32 v11, v11, v127
	v_mul_f32_e32 v126, v80, v121
	v_fmac_f32_e32 v126, v12, v76
	v_add_f32_e32 v12, v125, v126
	v_lshlrev_b32_e32 v127, 16, v241
	v_mul_f32_e32 v12, v12, v127
	v_mul_f32_e32 v126, v81, v121
	v_fmac_f32_e32 v126, v13, v77
	v_add_f32_e32 v13, v125, v126
	v_and_b32_e32 v127, 0xffff0000, v241
	v_mul_f32_e32 v13, v13, v127
	v_cvt_pk_bf16_f32 v10, v10, v11
	v_cvt_pk_bf16_f32 v11, v12, v13
	ds_write_b64 v130, v[10:11] offset:6144
	v_mul_f32_e32 v126, v70, v121
	v_fmac_f32_e32 v126, v14, v66
	v_add_f32_e32 v14, v125, v126
	v_lshlrev_b32_e32 v127, 16, v246
	v_mul_f32_e32 v14, v14, v127
	v_mul_f32_e32 v126, v71, v121
	v_fmac_f32_e32 v126, v15, v67
	v_add_f32_e32 v15, v125, v126
	v_and_b32_e32 v127, 0xffff0000, v246
	v_mul_f32_e32 v15, v15, v127
	v_mul_f32_e32 v126, v72, v121
	v_fmac_f32_e32 v126, v16, v68
	v_add_f32_e32 v16, v125, v126
	v_lshlrev_b32_e32 v127, 16, v247
	v_mul_f32_e32 v16, v16, v127
	v_mul_f32_e32 v126, v73, v121
	v_fmac_f32_e32 v126, v17, v69
	v_add_f32_e32 v17, v125, v126
	v_and_b32_e32 v127, 0xffff0000, v247
	v_mul_f32_e32 v17, v17, v127
	v_cvt_pk_bf16_f32 v14, v14, v15
	v_cvt_pk_bf16_f32 v15, v16, v17
	ds_write_b64 v131, v[14:15] offset:6144
	s_waitcnt lgkmcnt(0)
	ds_read_b128 v[2:5], v132 offset:0
	ds_read_b128 v[6:9], v132 offset:1024
	ds_read_b128 v[10:13], v132 offset:2048
	ds_read_b128 v[14:17], v132 offset:3072
	ds_read_b128 v[18:21], v132 offset:4096
	ds_read_b128 v[22:25], v132 offset:5120
	ds_read_b128 v[26:29], v132 offset:6144
	ds_read_b128 v[30:33], v132 offset:7168
	s_waitcnt lgkmcnt(7)
	global_store_dwordx4 v133, v[2:5], s[62:63] offset:1536
	v_add_u32_e32 v127, 0x8000, v133
	s_waitcnt lgkmcnt(6)
	global_store_dwordx4 v127, v[6:9], s[62:63] offset:1536
	v_add_u32_e32 v126, 0x10000, v133
	s_waitcnt lgkmcnt(5)
	global_store_dwordx4 v126, v[10:13], s[62:63] offset:1536
	v_add_u32_e32 v127, 0x18000, v133
	s_waitcnt lgkmcnt(4)
	global_store_dwordx4 v127, v[14:17], s[62:63] offset:1536
	v_add_u32_e32 v126, 0x20000, v133
	s_waitcnt lgkmcnt(3)
	global_store_dwordx4 v126, v[18:21], s[62:63] offset:1536
	v_add_u32_e32 v127, 0x28000, v133
	s_waitcnt lgkmcnt(2)
	global_store_dwordx4 v127, v[22:25], s[62:63] offset:1536
	v_add_u32_e32 v126, 0x30000, v133
	s_waitcnt lgkmcnt(1)
	global_store_dwordx4 v126, v[26:29], s[62:63] offset:1536
	v_add_u32_e32 v127, 0x38000, v133
	s_waitcnt lgkmcnt(0)
	global_store_dwordx4 v127, v[30:33], s[62:63] offset:1536
	s_barrier
	s_cbranch_scc0 .LBB0_849
